# GEMM K-loops: 30 LDS-DMA loads take scalar base + 32-bit lane offset directly (64-bit VALU address adds deleted)
# speedup vs baseline: 1.0038x; 1.0038x over previous
; #define PG8_STAGE(bufoff, gbase, voff) do { _Pragma("unroll") for (int _i = 0; _i < 2; ++_i) \
;         __builtin_amdgcn_global_load_lds((const unsigned*)((const char*)(gbase) + (voff)[_i]), (PG8_LAS unsigned*)(lds + (bufoff) + ldsw + _i * 8192), 16, 0, 0); } while (0)
; #define PG8_LDA(dst, b, h) do { _Pragma("unroll") for (int m = 0; m < 4; ++m) _Pragma("unroll") for (int k = 0; k < 2; ++k) dst[m][k] = *(const PG8_LAS bf16x8*)(lds + PG8_SA(b, h) + aoff + m * 2048 + k * 1024); } while (0)
; #define PG8_LDB(dst, b, h) do { _Pragma("unroll") for (int n = 0; n < 2; ++n) _Pragma("unroll") for (int k = 0; k < 2; ++k) dst[n][k] = *(const PG8_LAS bf16x8*)(lds + PG8_SB(b, h) + boff + n * 2048 + k * 1024); } while (0)
; #define PG8_MMA(ai, bj, At, Bt) do { __builtin_amdgcn_s_setprio(1); _Pragma("unroll") for (int m = 0; m < 4; ++m) _Pragma("unroll") for (int n = 0; n < 2; ++n) _Pragma("unroll") for (int k = 0; k < 2; ++k) \
;         acc[ai][bj][m][n] = __builtin_amdgcn_mfma_f32_16x16x32_bf16(Bt[n][k], At[m][k], acc[ai][bj][m][n], 0, 0, 0); __builtin_amdgcn_s_setprio(0); } while (0)
; #define PG8_WAIT_V(n) asm volatile("s_waitcnt vmcnt(" #n ")" ::: "memory")
; #define PG8_WAIT_L(n) asm volatile("s_waitcnt lgkmcnt(" #n ")" ::: "memory")
; #define PG8_BAR __builtin_amdgcn_s_barrier()
; #define PG8_SCHED __builtin_amdgcn_sched_barrier(0)
; template <class Epi, class Sched, bool ALIGN_EPI = false, bool SP2 = false>
; __device__ __forceinline__ void gemm_phase(PG8_LAS unsigned char* lds, const Gemm g, const Sched& S, const Epi& E) {
;     ...
;             PG8_LDB(B0, 0, 0); PG8_LDB(B1, 0, 1); PG8_SCHED; PG8_LDA(At, 0, 0); PG8_STAGE(PG8_SA(1, 1), a1 + hstep, voffA);
;             PG8_WAIT_V(8); PG8_WAIT_L(0); PG8_BAR; PG8_MMA(0, 0, At, B0); PG8_MMA(0, 1, At, B1); PG8_BAR; PG8_SCHED;
;             PG8_LDA(At, 0, 1); PG8_STAGE(PG8_SB(0, 0), b2, voffB); PG8_STAGE(PG8_SB(0, 1), b2 + hstep, voffB); PG8_STAGE(PG8_SA(0, 0), a2, voffA);
;             PG8_WAIT_V(8); PG8_WAIT_L(0); PG8_BAR; PG8_MMA(1, 0, At, B0); PG8_MMA(1, 1, At, B1); PG8_BAR; PG8_SCHED;
.LBB0_97:
	s_add_u32 s24, s22, 0xfffc0080
	s_addc_u32 s25, s23, -1
	s_add_i32 s52, 0, 0x10000
	s_cmp_eq_u32 vcc_lo, 12
	s_cselect_b32 s27, s17, s25
	s_cselect_b32 s26, s44, s24
	s_cselect_b32 s25, s15, s47
	s_cselect_b32 s24, s45, s46
	s_add_i32 s53, 0, 0x14000
	v_add_u32_e32 v152, s52, v175
	v_add_u32_e32 v162, s53, v175
	ds_read_b128 v[0:3], v152
	ds_read_b128 v[4:7], v152 offset:1024
	ds_read_b128 v[148:151], v152 offset:2048
	ds_read_b128 v[152:155], v152 offset:3072
	ds_read_b128 v[156:159], v162
	ds_read_b128 v[182:185], v162 offset:1024
	ds_read_b128 v[186:189], v162 offset:2048
	ds_read_b128 v[190:193], v162 offset:3072
	s_add_i32 m0, s65, 0xc000
	ds_read_b128 v[194:197], v180
	ds_read_b128 v[198:201], v180 offset:1024
	ds_read_b128 v[202:205], v180 offset:2048
	ds_read_b128 v[206:209], v180 offset:3072
	ds_read_b128 v[210:213], v180 offset:4096
	ds_read_b128 v[214:217], v180 offset:5120
	ds_read_b128 v[218:221], v180 offset:6144
	ds_read_b128 v[232:235], v180 offset:7168
	global_load_lds_dwordx4 v144, s[22:23]
	s_add_i32 m0, s65, 0xe000
	s_nop 0
	global_load_lds_dwordx4 v146, s[22:23]
	s_waitcnt vmcnt(8)
	s_waitcnt lgkmcnt(0)
	s_barrier
	s_setprio 1
	s_waitcnt lgkmcnt(0)
	v_mfma_f32_16x16x32_bf16 v[132:135], v[0:3], v[194:197], v[132:135]
	v_mfma_f32_16x16x32_bf16 v[124:127], v[148:151], v[194:197], v[124:127]
	v_mfma_f32_16x16x32_bf16 v[116:119], v[0:3], v[202:205], v[116:119]
	v_mfma_f32_16x16x32_bf16 v[108:111], v[148:151], v[202:205], v[108:111]
	v_mfma_f32_16x16x32_bf16 v[100:103], v[0:3], v[210:213], v[100:103]
	v_mfma_f32_16x16x32_bf16 v[92:95], v[148:151], v[210:213], v[92:95]
	v_mfma_f32_16x16x32_bf16 v[84:87], v[0:3], v[218:221], v[84:87]
	v_mfma_f32_16x16x32_bf16 v[76:79], v[148:151], v[218:221], v[76:79]
	v_mfma_f32_16x16x32_bf16 v[132:135], v[4:7], v[198:201], v[132:135]
	v_mfma_f32_16x16x32_bf16 v[124:127], v[152:155], v[198:201], v[124:127]
	v_mfma_f32_16x16x32_bf16 v[116:119], v[4:7], v[206:209], v[116:119]
	v_mfma_f32_16x16x32_bf16 v[108:111], v[152:155], v[206:209], v[108:111]
	v_mfma_f32_16x16x32_bf16 v[100:103], v[4:7], v[214:217], v[100:103]
	v_mfma_f32_16x16x32_bf16 v[92:95], v[152:155], v[214:217], v[92:95]
	v_mfma_f32_16x16x32_bf16 v[84:87], v[4:7], v[232:235], v[84:87]
	v_mfma_f32_16x16x32_bf16 v[76:79], v[152:155], v[232:235], v[76:79]
	s_setprio 0
	s_setprio 1
	v_mfma_f32_16x16x32_bf16 v[128:131], v[156:159], v[194:197], v[128:131]
	v_mfma_f32_16x16x32_bf16 v[120:123], v[186:189], v[194:197], v[120:123]
	v_mfma_f32_16x16x32_bf16 v[112:115], v[156:159], v[202:205], v[112:115]
	v_mfma_f32_16x16x32_bf16 v[104:107], v[186:189], v[202:205], v[104:107]
	v_mfma_f32_16x16x32_bf16 v[96:99], v[156:159], v[210:213], v[96:99]
	v_mfma_f32_16x16x32_bf16 v[88:91], v[186:189], v[210:213], v[88:91]
	v_mfma_f32_16x16x32_bf16 v[80:83], v[156:159], v[218:221], v[80:83]
	v_mfma_f32_16x16x32_bf16 v[72:75], v[186:189], v[218:221], v[72:75]
	v_mfma_f32_16x16x32_bf16 v[128:131], v[182:185], v[198:201], v[128:131]
	v_mfma_f32_16x16x32_bf16 v[120:123], v[190:193], v[198:201], v[120:123]
	v_mfma_f32_16x16x32_bf16 v[112:115], v[182:185], v[206:209], v[112:115]
	v_mfma_f32_16x16x32_bf16 v[104:107], v[190:193], v[206:209], v[104:107]
	v_mfma_f32_16x16x32_bf16 v[96:99], v[182:185], v[214:217], v[96:99]
	v_mfma_f32_16x16x32_bf16 v[88:91], v[190:193], v[214:217], v[88:91]
	v_mfma_f32_16x16x32_bf16 v[80:83], v[182:185], v[232:235], v[80:83]
	v_mfma_f32_16x16x32_bf16 v[72:75], v[190:193], v[232:235], v[72:75]
	s_setprio 0
	s_barrier
	s_add_i32 s52, s52, s29
	v_lshl_add_u64 v[176:177], s[24:25], 0, v[160:161]
	s_mov_b32 m0, s52
	ds_read_b128 v[194:197], v180 offset:16384
	ds_read_b128 v[198:201], v180 offset:17408
	ds_read_b128 v[202:205], v180 offset:18432
	ds_read_b128 v[206:209], v180 offset:19456
	ds_read_b128 v[210:213], v180 offset:20480
	ds_read_b128 v[214:217], v180 offset:21504
	ds_read_b128 v[218:221], v180 offset:22528
	ds_read_b128 v[232:235], v180 offset:23552
	global_load_lds_dwordx4 v[176:177], off
	s_add_i32 m0, s52, 0x2000
	s_add_u32 s68, s24, 0x40000
	v_lshl_add_u64 v[222:223], s[24:25], 0, v[136:137]
	s_addc_u32 s69, s25, 0
	s_add_i32 s52, s53, s29
	global_load_lds_dwordx4 v[222:223], off
	s_mov_b32 m0, s52
	v_lshl_add_u64 v[238:239], s[26:27], 0, v[138:139]
	global_load_lds_dwordx4 v160, s[68:69]
	s_add_i32 m0, s52, 0x2000
	s_nop 0
	global_load_lds_dwordx4 v136, s[68:69]
	v_lshl_add_u64 v[236:237], s[26:27], 0, v[140:141]
	s_mov_b32 m0, s65
	s_nop 0
	global_load_lds_dwordx4 v[236:237], off
	s_mov_b32 m0, s76
	s_nop 0
	global_load_lds_dwordx4 v[238:239], off
	s_waitcnt vmcnt(8)
	s_waitcnt lgkmcnt(0)
	s_barrier
; #define PG8_STAGE(bufoff, gbase, voff) do { _Pragma("unroll") for (int _i = 0; _i < 2; ++_i) \
;         __builtin_amdgcn_global_load_lds((const unsigned*)((const char*)(gbase) + (voff)[_i]), (PG8_LAS unsigned*)(lds + (bufoff) + ldsw + _i * 8192), 16, 0, 0); } while (0)
; #define PG8_LDA(dst, b, h) do { _Pragma("unroll") for (int m = 0; m < 4; ++m) _Pragma("unroll") for (int k = 0; k < 2; ++k) dst[m][k] = *(const PG8_LAS bf16x8*)(lds + PG8_SA(b, h) + aoff + m * 2048 + k * 1024); } while (0)
; #define PG8_LDB(dst, b, h) do { _Pragma("unroll") for (int n = 0; n < 2; ++n) _Pragma("unroll") for (int k = 0; k < 2; ++k) dst[n][k] = *(const PG8_LAS bf16x8*)(lds + PG8_SB(b, h) + boff + n * 2048 + k * 1024); } while (0)
; #define PG8_MMA(ai, bj, At, Bt) do { __builtin_amdgcn_s_setprio(1); _Pragma("unroll") for (int m = 0; m < 4; ++m) _Pragma("unroll") for (int n = 0; n < 2; ++n) _Pragma("unroll") for (int k = 0; k < 2; ++k) \
;         acc[ai][bj][m][n] = __builtin_amdgcn_mfma_f32_16x16x32_bf16(Bt[n][k], At[m][k], acc[ai][bj][m][n], 0, 0, 0); __builtin_amdgcn_s_setprio(0); } while (0)
; #define PG8_WAIT_V(n) asm volatile("s_waitcnt vmcnt(" #n ")" ::: "memory")
; #define PG8_WAIT_L(n) asm volatile("s_waitcnt lgkmcnt(" #n ")" ::: "memory")
; #define PG8_BAR __builtin_amdgcn_s_barrier()
; #define PG8_SCHED __builtin_amdgcn_sched_barrier(0)
; template <class Epi, class Sched, bool ALIGN_EPI = false, bool SP2 = false>
; __device__ __forceinline__ void gemm_phase(PG8_LAS unsigned char* lds, const Gemm g, const Sched& S, const Epi& E) {
;     ...
;             PG8_WAIT_V(8); PG8_WAIT_L(0); PG8_BAR; PG8_MMA(1, 0, At, B0); PG8_MMA(1, 1, At, B1); PG8_BAR; PG8_SCHED;
;             PG8_LDB(B0, 1, 0); PG8_LDB(B1, 1, 1); PG8_SCHED; PG8_LDA(At, 1, 0); PG8_STAGE(PG8_SA(0, 1), a2 + hstep, voffA);
;             PG8_WAIT_V(8); PG8_WAIT_L(0); PG8_BAR; PG8_MMA(0, 0, At, B0); PG8_MMA(0, 1, At, B1); PG8_BAR; PG8_SCHED;
;             PG8_LDA(At, 1, 1); PG8_STAGE(PG8_SB(1, 0), b3, voffB); PG8_STAGE(PG8_SB(1, 1), b3 + hstep, voffB); PG8_STAGE(PG8_SA(1, 0), a3, voffA);
	s_setprio 1
	s_waitcnt lgkmcnt(0)
	v_mfma_f32_16x16x32_bf16 v[68:71], v[0:3], v[194:197], v[68:71]
	v_mfma_f32_16x16x32_bf16 v[60:63], v[148:151], v[194:197], v[60:63]
	v_mfma_f32_16x16x32_bf16 v[52:55], v[0:3], v[202:205], v[52:55]
	v_mfma_f32_16x16x32_bf16 v[44:47], v[148:151], v[202:205], v[44:47]
	v_mfma_f32_16x16x32_bf16 v[36:39], v[0:3], v[210:213], v[36:39]
	v_mfma_f32_16x16x32_bf16 v[28:31], v[148:151], v[210:213], v[28:31]
	v_mfma_f32_16x16x32_bf16 v[0:3], v[0:3], v[218:221], v[20:23]
	v_mfma_f32_16x16x32_bf16 v[68:71], v[4:7], v[198:201], v[68:71]
	v_mfma_f32_16x16x32_bf16 v[60:63], v[152:155], v[198:201], v[60:63]
	v_mfma_f32_16x16x32_bf16 v[52:55], v[4:7], v[206:209], v[52:55]
	v_mfma_f32_16x16x32_bf16 v[44:47], v[152:155], v[206:209], v[44:47]
	v_mfma_f32_16x16x32_bf16 v[36:39], v[4:7], v[214:217], v[36:39]
	v_mfma_f32_16x16x32_bf16 v[28:31], v[152:155], v[214:217], v[28:31]
	v_mfma_f32_16x16x32_bf16 v[0:3], v[4:7], v[232:235], v[0:3]
	v_mfma_f32_16x16x32_bf16 v[4:7], v[148:151], v[218:221], v[12:15]
	v_mfma_f32_16x16x32_bf16 v[4:7], v[152:155], v[232:235], v[4:7]
	s_setprio 0
	s_setprio 1
	v_mfma_f32_16x16x32_bf16 v[12:15], v[156:159], v[194:197], v[64:67]
	v_mfma_f32_16x16x32_bf16 v[64:67], v[182:185], v[198:201], v[12:15]
	v_mfma_f32_16x16x32_bf16 v[12:15], v[186:189], v[194:197], v[56:59]
	v_mfma_f32_16x16x32_bf16 v[56:59], v[190:193], v[198:201], v[12:15]
	v_mfma_f32_16x16x32_bf16 v[12:15], v[156:159], v[202:205], v[48:51]
	v_mfma_f32_16x16x32_bf16 v[48:51], v[182:185], v[206:209], v[12:15]
	v_mfma_f32_16x16x32_bf16 v[12:15], v[186:189], v[202:205], v[40:43]
	v_mfma_f32_16x16x32_bf16 v[40:43], v[190:193], v[206:209], v[12:15]
	v_mfma_f32_16x16x32_bf16 v[12:15], v[156:159], v[210:213], v[32:35]
	v_mfma_f32_16x16x32_bf16 v[32:35], v[182:185], v[214:217], v[12:15]
	v_mfma_f32_16x16x32_bf16 v[12:15], v[186:189], v[210:213], v[24:27]
	v_mfma_f32_16x16x32_bf16 v[24:27], v[190:193], v[214:217], v[12:15]
	v_mfma_f32_16x16x32_bf16 v[12:15], v[156:159], v[218:221], v[16:19]
	v_mfma_f32_16x16x32_bf16 v[8:11], v[186:189], v[218:221], v[8:11]
	v_mfma_f32_16x16x32_bf16 v[16:19], v[182:185], v[232:235], v[12:15]
	v_mfma_f32_16x16x32_bf16 v[8:11], v[190:193], v[232:235], v[8:11]
	s_setprio 0
	s_barrier
	s_add_i32 s52, 0, 0x18000
	s_add_i32 s53, 0, 0x1c000
	v_add_u32_e32 v152, s52, v175
	v_add_u32_e32 v162, s53, v175
	ds_read_b128 v[12:15], v152
	ds_read_b128 v[20:23], v152 offset:1024
	ds_read_b128 v[148:151], v152 offset:2048
	ds_read_b128 v[152:155], v152 offset:3072
	ds_read_b128 v[156:159], v162
	ds_read_b128 v[182:185], v162 offset:1024
	ds_read_b128 v[186:189], v162 offset:2048
	ds_read_b128 v[190:193], v162 offset:3072
	s_add_u32 s26, s26, 0x40000
	s_addc_u32 s27, s27, 0
	s_mov_b32 m0, s86
	ds_read_b128 v[194:197], v180 offset:32768
	ds_read_b128 v[198:201], v180 offset:33792
	ds_read_b128 v[202:205], v180 offset:34816
	ds_read_b128 v[206:209], v180 offset:35840
	ds_read_b128 v[210:213], v180 offset:36864
	ds_read_b128 v[214:217], v180 offset:37888
	ds_read_b128 v[218:221], v180 offset:38912
	ds_read_b128 v[232:235], v180 offset:39936
	global_load_lds_dwordx4 v140, s[26:27]
	s_mov_b32 m0, s87
	s_nop 0
	global_load_lds_dwordx4 v138, s[26:27]
	s_waitcnt vmcnt(8)
	s_waitcnt lgkmcnt(0)
	s_barrier
	s_setprio 1
	s_waitcnt lgkmcnt(0)
	v_mfma_f32_16x16x32_bf16 v[132:135], v[12:15], v[194:197], v[132:135]
	v_mfma_f32_16x16x32_bf16 v[124:127], v[148:151], v[194:197], v[124:127]
	v_mfma_f32_16x16x32_bf16 v[116:119], v[12:15], v[202:205], v[116:119]
	v_mfma_f32_16x16x32_bf16 v[108:111], v[148:151], v[202:205], v[108:111]
	v_mfma_f32_16x16x32_bf16 v[100:103], v[12:15], v[210:213], v[100:103]
	v_mfma_f32_16x16x32_bf16 v[92:95], v[148:151], v[210:213], v[92:95]
	v_mfma_f32_16x16x32_bf16 v[84:87], v[12:15], v[218:221], v[84:87]
	v_mfma_f32_16x16x32_bf16 v[76:79], v[148:151], v[218:221], v[76:79]
	v_mfma_f32_16x16x32_bf16 v[132:135], v[20:23], v[198:201], v[132:135]
	v_mfma_f32_16x16x32_bf16 v[124:127], v[152:155], v[198:201], v[124:127]
	v_mfma_f32_16x16x32_bf16 v[116:119], v[20:23], v[206:209], v[116:119]
	v_mfma_f32_16x16x32_bf16 v[108:111], v[152:155], v[206:209], v[108:111]
	v_mfma_f32_16x16x32_bf16 v[100:103], v[20:23], v[214:217], v[100:103]
	v_mfma_f32_16x16x32_bf16 v[92:95], v[152:155], v[214:217], v[92:95]
	v_mfma_f32_16x16x32_bf16 v[84:87], v[20:23], v[232:235], v[84:87]
	v_mfma_f32_16x16x32_bf16 v[76:79], v[152:155], v[232:235], v[76:79]
	s_setprio 0
	s_setprio 1
	v_mfma_f32_16x16x32_bf16 v[128:131], v[156:159], v[194:197], v[128:131]
	v_mfma_f32_16x16x32_bf16 v[120:123], v[186:189], v[194:197], v[120:123]
	v_mfma_f32_16x16x32_bf16 v[112:115], v[156:159], v[202:205], v[112:115]
	v_mfma_f32_16x16x32_bf16 v[104:107], v[186:189], v[202:205], v[104:107]
	v_mfma_f32_16x16x32_bf16 v[96:99], v[156:159], v[210:213], v[96:99]
	v_mfma_f32_16x16x32_bf16 v[88:91], v[186:189], v[210:213], v[88:91]
	v_mfma_f32_16x16x32_bf16 v[80:83], v[156:159], v[218:221], v[80:83]
	v_mfma_f32_16x16x32_bf16 v[72:75], v[186:189], v[218:221], v[72:75]
	v_mfma_f32_16x16x32_bf16 v[128:131], v[182:185], v[198:201], v[128:131]
	v_mfma_f32_16x16x32_bf16 v[120:123], v[190:193], v[198:201], v[120:123]
	v_mfma_f32_16x16x32_bf16 v[112:115], v[182:185], v[206:209], v[112:115]
	v_mfma_f32_16x16x32_bf16 v[104:107], v[190:193], v[206:209], v[104:107]
	v_mfma_f32_16x16x32_bf16 v[96:99], v[182:185], v[214:217], v[96:99]
	v_mfma_f32_16x16x32_bf16 v[88:91], v[190:193], v[214:217], v[88:91]
	v_mfma_f32_16x16x32_bf16 v[80:83], v[182:185], v[232:235], v[80:83]
	v_mfma_f32_16x16x32_bf16 v[72:75], v[190:193], v[232:235], v[72:75]
	s_setprio 0
	s_barrier
; #define PG8_STAGE(bufoff, gbase, voff) do { _Pragma("unroll") for (int _i = 0; _i < 2; ++_i) \
;         __builtin_amdgcn_global_load_lds((const unsigned*)((const char*)(gbase) + (voff)[_i]), (PG8_LAS unsigned*)(lds + (bufoff) + ldsw + _i * 8192), 16, 0, 0); } while (0)
; #define PG8_LDA(dst, b, h) do { _Pragma("unroll") for (int m = 0; m < 4; ++m) _Pragma("unroll") for (int k = 0; k < 2; ++k) dst[m][k] = *(const PG8_LAS bf16x8*)(lds + PG8_SA(b, h) + aoff + m * 2048 + k * 1024); } while (0)
; #define PG8_MMA(ai, bj, At, Bt) do { __builtin_amdgcn_s_setprio(1); _Pragma("unroll") for (int m = 0; m < 4; ++m) _Pragma("unroll") for (int n = 0; n < 2; ++n) _Pragma("unroll") for (int k = 0; k < 2; ++k) \
;         acc[ai][bj][m][n] = __builtin_amdgcn_mfma_f32_16x16x32_bf16(Bt[n][k], At[m][k], acc[ai][bj][m][n], 0, 0, 0); __builtin_amdgcn_s_setprio(0); } while (0)
; #define PG8_WAIT_V(n) asm volatile("s_waitcnt vmcnt(" #n ")" ::: "memory")
; #define PG8_WAIT_L(n) asm volatile("s_waitcnt lgkmcnt(" #n ")" ::: "memory")
; #define PG8_BAR __builtin_amdgcn_s_barrier()
; #define PG8_SCHED __builtin_amdgcn_sched_barrier(0)
; template <class Epi, class Sched, bool ALIGN_EPI = false, bool SP2 = false>
; __device__ __forceinline__ void gemm_phase(PG8_LAS unsigned char* lds, const Gemm g, const Sched& S, const Epi& E) {
;     ...
;         for (int t = 0; t < nt; t += 2) {
;             const bool last = (t == nt - 2);
;             const char* a1 = cA + (size_t)(t + 1) * kstep;
;             const char* a2 = last ? nA : cA + (size_t)(t + 2) * kstep; const char* b2 = last ? nB : cB + (size_t)(t + 2) * kstep;
;     ...
;             PG8_LDA(At, 1, 1); PG8_STAGE(PG8_SB(1, 0), b3, voffB); PG8_STAGE(PG8_SB(1, 1), b3 + hstep, voffB); PG8_STAGE(PG8_SA(1, 0), a3, voffA);
;             PG8_WAIT_V(8); PG8_WAIT_L(0); PG8_BAR; PG8_MMA(1, 0, At, B0); PG8_MMA(1, 1, At, B1); PG8_BAR; PG8_SCHED;
	s_add_i32 s26, s52, s29
	v_lshl_add_u64 v[176:177], v[176:177], 0, s[50:51]
	s_mov_b32 m0, s26
	ds_read_b128 v[194:197], v180 offset:49152
	ds_read_b128 v[198:201], v180 offset:50176
	ds_read_b128 v[202:205], v180 offset:51200
	ds_read_b128 v[206:209], v180 offset:52224
	ds_read_b128 v[210:213], v180 offset:53248
	ds_read_b128 v[214:217], v180 offset:54272
	ds_read_b128 v[218:221], v180 offset:55296
	ds_read_b128 v[232:235], v180 offset:56320
	global_load_lds_dwordx4 v[176:177], off
	s_add_i32 m0, s26, 0x2000
	s_add_u32 s24, s24, 0x40080
	v_lshl_add_u64 v[176:177], v[222:223], 0, s[50:51]
	s_addc_u32 s25, s25, 0
	s_add_i32 s26, s53, s29
	global_load_lds_dwordx4 v[176:177], off
	s_mov_b32 m0, s26
	s_nop 0
	global_load_lds_dwordx4 v160, s[24:25]
	s_add_i32 m0, s26, 0x2000
	s_nop 0
	global_load_lds_dwordx4 v136, s[24:25]
	v_lshl_add_u64 v[176:177], v[236:237], 0, s[50:51]
	s_mov_b32 m0, s0
	s_nop 0
	global_load_lds_dwordx4 v[176:177], off
	v_lshl_add_u64 v[176:177], v[238:239], 0, s[50:51]
	s_mov_b32 m0, s40
	s_nop 0
	global_load_lds_dwordx4 v[176:177], off
	s_waitcnt vmcnt(8)
	s_waitcnt lgkmcnt(0)
	s_barrier
	s_setprio 1
	s_waitcnt lgkmcnt(0)
	v_mfma_f32_16x16x32_bf16 v[68:71], v[12:15], v[194:197], v[68:71]
	v_mfma_f32_16x16x32_bf16 v[52:55], v[12:15], v[202:205], v[52:55]
	v_mfma_f32_16x16x32_bf16 v[36:39], v[12:15], v[210:213], v[36:39]
	v_mfma_f32_16x16x32_bf16 v[0:3], v[12:15], v[218:221], v[0:3]
	v_mfma_f32_16x16x32_bf16 v[68:71], v[20:23], v[198:201], v[68:71]
	v_mfma_f32_16x16x32_bf16 v[60:63], v[148:151], v[194:197], v[60:63]
	v_mfma_f32_16x16x32_bf16 v[52:55], v[20:23], v[206:209], v[52:55]
	v_mfma_f32_16x16x32_bf16 v[44:47], v[148:151], v[202:205], v[44:47]
	v_mfma_f32_16x16x32_bf16 v[36:39], v[20:23], v[214:217], v[36:39]
	v_mfma_f32_16x16x32_bf16 v[28:31], v[148:151], v[210:213], v[28:31]
	v_mfma_f32_16x16x32_bf16 v[20:23], v[20:23], v[232:235], v[0:3]
	v_mfma_f32_16x16x32_bf16 v[0:3], v[148:151], v[218:221], v[4:7]
	v_mfma_f32_16x16x32_bf16 v[60:63], v[152:155], v[198:201], v[60:63]
	v_mfma_f32_16x16x32_bf16 v[44:47], v[152:155], v[206:209], v[44:47]
	v_mfma_f32_16x16x32_bf16 v[28:31], v[152:155], v[214:217], v[28:31]
	v_mfma_f32_16x16x32_bf16 v[12:15], v[152:155], v[232:235], v[0:3]
	s_setprio 0
	s_setprio 1
	v_mfma_f32_16x16x32_bf16 v[0:3], v[156:159], v[194:197], v[64:67]
	v_mfma_f32_16x16x32_bf16 v[64:67], v[182:185], v[198:201], v[0:3]
	v_mfma_f32_16x16x32_bf16 v[0:3], v[186:189], v[194:197], v[56:59]
	v_mfma_f32_16x16x32_bf16 v[56:59], v[190:193], v[198:201], v[0:3]
	v_mfma_f32_16x16x32_bf16 v[0:3], v[156:159], v[202:205], v[48:51]
	v_mfma_f32_16x16x32_bf16 v[48:51], v[182:185], v[206:209], v[0:3]
	v_mfma_f32_16x16x32_bf16 v[0:3], v[186:189], v[202:205], v[40:43]
	v_mfma_f32_16x16x32_bf16 v[40:43], v[190:193], v[206:209], v[0:3]
	v_mfma_f32_16x16x32_bf16 v[0:3], v[156:159], v[210:213], v[32:35]
	v_mfma_f32_16x16x32_bf16 v[32:35], v[182:185], v[214:217], v[0:3]
	v_mfma_f32_16x16x32_bf16 v[0:3], v[186:189], v[210:213], v[24:27]
	v_mfma_f32_16x16x32_bf16 v[24:27], v[190:193], v[214:217], v[0:3]
	v_mfma_f32_16x16x32_bf16 v[0:3], v[156:159], v[218:221], v[16:19]
	v_mfma_f32_16x16x32_bf16 v[16:19], v[182:185], v[232:235], v[0:3]
	v_mfma_f32_16x16x32_bf16 v[0:3], v[186:189], v[218:221], v[8:11]
	v_mfma_f32_16x16x32_bf16 v[8:11], v[190:193], v[232:235], v[0:3]
	s_setprio 0
	s_barrier
	s_add_i32 vcc_lo, vcc_lo, 2
	s_add_u32 s22, s22, 0x100
	s_addc_u32 s23, s23, 0
	s_add_u32 s46, s46, 0x100
	s_addc_u32 s47, s47, 0
	s_cmp_gt_u32 vcc_lo, 13
	s_cbranch_scc0 .LBB0_97
	s_and_b64 vcc, exec, s[12:13]
	s_cbranch_vccz .LBB0_100
	s_barrier

; #define PG8_STAGE(bufoff, gbase, voff) do { _Pragma("unroll") for (int _i = 0; _i < 2; ++_i) \
;         __builtin_amdgcn_global_load_lds((const unsigned*)((const char*)(gbase) + (voff)[_i]), (PG8_LAS unsigned*)(lds + (bufoff) + ldsw + _i * 8192), 16, 0, 0); } while (0)
; #define PG8_LDA(dst, b, h) do { _Pragma("unroll") for (int m = 0; m < 4; ++m) _Pragma("unroll") for (int k = 0; k < 2; ++k) dst[m][k] = *(const PG8_LAS bf16x8*)(lds + PG8_SA(b, h) + aoff + m * 2048 + k * 1024); } while (0)
; #define PG8_LDB(dst, b, h) do { _Pragma("unroll") for (int n = 0; n < 2; ++n) _Pragma("unroll") for (int k = 0; k < 2; ++k) dst[n][k] = *(const PG8_LAS bf16x8*)(lds + PG8_SB(b, h) + boff + n * 2048 + k * 1024); } while (0)
; #define PG8_MMA(ai, bj, At, Bt) do { __builtin_amdgcn_s_setprio(1); _Pragma("unroll") for (int m = 0; m < 4; ++m) _Pragma("unroll") for (int n = 0; n < 2; ++n) _Pragma("unroll") for (int k = 0; k < 2; ++k) \
;         acc[ai][bj][m][n] = __builtin_amdgcn_mfma_f32_16x16x32_bf16(Bt[n][k], At[m][k], acc[ai][bj][m][n], 0, 0, 0); __builtin_amdgcn_s_setprio(0); } while (0)
; #define PG8_WAIT_V(n) asm volatile("s_waitcnt vmcnt(" #n ")" ::: "memory")
; #define PG8_WAIT_L(n) asm volatile("s_waitcnt lgkmcnt(" #n ")" ::: "memory")
; #define PG8_BAR __builtin_amdgcn_s_barrier()
; #define PG8_SCHED __builtin_amdgcn_sched_barrier(0)
; template <class Epi, class Sched, bool ALIGN_EPI = false, bool SP2 = false>
; __device__ __forceinline__ void gemm_phase(PG8_LAS unsigned char* lds, const Gemm g, const Sched& S, const Epi& E) {
;     ...
;             PG8_LDB(B0, 0, 0); PG8_LDB(B1, 0, 1); PG8_SCHED; PG8_LDA(At, 0, 0); PG8_STAGE(PG8_SA(1, 1), a1 + hstep, voffA);
;             PG8_WAIT_V(8); PG8_WAIT_L(0); PG8_BAR; PG8_MMA(0, 0, At, B0); PG8_MMA(0, 1, At, B1); PG8_BAR; PG8_SCHED;
;             PG8_LDA(At, 0, 1); PG8_STAGE(PG8_SB(0, 0), b2, voffB); PG8_STAGE(PG8_SB(0, 1), b2 + hstep, voffB); PG8_STAGE(PG8_SA(0, 0), a2, voffA);
;             PG8_WAIT_V(8); PG8_WAIT_L(0); PG8_BAR; PG8_MMA(1, 0, At, B0); PG8_MMA(1, 1, At, B1); PG8_BAR; PG8_SCHED;
.LBB0_177:
	s_add_u32 s24, s22, 0x100
	s_addc_u32 s25, s23, 0
	s_add_i32 s52, 0, 0x10000
	s_cmp_eq_u32 s68, 40
	s_cselect_b32 s29, s9, s25
	s_cselect_b32 s28, s8, s24
	s_cselect_b32 s27, s21, vcc_hi
	s_cselect_b32 s26, s20, vcc_lo
	s_add_i32 s53, 0, 0x14000
	v_add_u32_e32 v140, s52, v175
	v_add_u32_e32 v162, s53, v175
	ds_read_b128 v[128:131], v140
	ds_read_b128 v[132:135], v140 offset:1024
	ds_read_b128 v[136:139], v140 offset:2048
	ds_read_b128 v[140:143], v140 offset:3072
	ds_read_b128 v[144:147], v162
	ds_read_b128 v[148:151], v162 offset:1024
	ds_read_b128 v[178:181], v162 offset:2048
	ds_read_b128 v[182:185], v162 offset:3072
	v_lshl_add_u64 v[218:219], s[22:23], 0, v[158:159]
	s_add_i32 m0, s41, 0xc000
	ds_read_b128 v[186:189], v233
	ds_read_b128 v[190:193], v233 offset:1024
	ds_read_b128 v[194:197], v233 offset:2048
	ds_read_b128 v[198:201], v233 offset:3072
	ds_read_b128 v[202:205], v233 offset:4096
	ds_read_b128 v[206:209], v233 offset:5120
	ds_read_b128 v[210:213], v233 offset:6144
	ds_read_b128 v[214:217], v233 offset:7168
	global_load_lds_dwordx4 v[218:219], off
	v_lshl_add_u64 v[218:219], s[22:23], 0, v[176:177]
	s_add_i32 m0, s41, 0xe000
	s_nop 0
	global_load_lds_dwordx4 v[218:219], off
	s_waitcnt vmcnt(8)
	s_waitcnt lgkmcnt(0)
	s_barrier
	s_setprio 1
	s_waitcnt lgkmcnt(0)
	v_mfma_f32_16x16x32_bf16 v[124:127], v[128:131], v[186:189], v[124:127]
	v_mfma_f32_16x16x32_bf16 v[120:123], v[136:139], v[186:189], v[120:123]
	v_mfma_f32_16x16x32_bf16 v[108:111], v[128:131], v[194:197], v[108:111]
	v_mfma_f32_16x16x32_bf16 v[104:107], v[136:139], v[194:197], v[104:107]
	v_mfma_f32_16x16x32_bf16 v[92:95], v[128:131], v[202:205], v[92:95]
	v_mfma_f32_16x16x32_bf16 v[88:91], v[136:139], v[202:205], v[88:91]
	v_mfma_f32_16x16x32_bf16 v[76:79], v[128:131], v[210:213], v[76:79]
	v_mfma_f32_16x16x32_bf16 v[72:75], v[136:139], v[210:213], v[72:75]
	v_mfma_f32_16x16x32_bf16 v[124:127], v[132:135], v[190:193], v[124:127]
	v_mfma_f32_16x16x32_bf16 v[120:123], v[140:143], v[190:193], v[120:123]
	v_mfma_f32_16x16x32_bf16 v[108:111], v[132:135], v[198:201], v[108:111]
	v_mfma_f32_16x16x32_bf16 v[104:107], v[140:143], v[198:201], v[104:107]
	v_mfma_f32_16x16x32_bf16 v[92:95], v[132:135], v[206:209], v[92:95]
	v_mfma_f32_16x16x32_bf16 v[88:91], v[140:143], v[206:209], v[88:91]
	v_mfma_f32_16x16x32_bf16 v[76:79], v[132:135], v[214:217], v[76:79]
	v_mfma_f32_16x16x32_bf16 v[72:75], v[140:143], v[214:217], v[72:75]
	s_setprio 0
	s_setprio 1
	v_mfma_f32_16x16x32_bf16 v[116:119], v[144:147], v[186:189], v[116:119]
	v_mfma_f32_16x16x32_bf16 v[112:115], v[178:181], v[186:189], v[112:115]
	v_mfma_f32_16x16x32_bf16 v[100:103], v[144:147], v[194:197], v[100:103]
	v_mfma_f32_16x16x32_bf16 v[96:99], v[178:181], v[194:197], v[96:99]
	v_mfma_f32_16x16x32_bf16 v[84:87], v[144:147], v[202:205], v[84:87]
	v_mfma_f32_16x16x32_bf16 v[80:83], v[178:181], v[202:205], v[80:83]
	v_mfma_f32_16x16x32_bf16 v[68:71], v[144:147], v[210:213], v[68:71]
	v_mfma_f32_16x16x32_bf16 v[64:67], v[178:181], v[210:213], v[64:67]
	v_mfma_f32_16x16x32_bf16 v[116:119], v[148:151], v[190:193], v[116:119]
	v_mfma_f32_16x16x32_bf16 v[112:115], v[182:185], v[190:193], v[112:115]
	v_mfma_f32_16x16x32_bf16 v[100:103], v[148:151], v[198:201], v[100:103]
	v_mfma_f32_16x16x32_bf16 v[96:99], v[182:185], v[198:201], v[96:99]
	v_mfma_f32_16x16x32_bf16 v[84:87], v[148:151], v[206:209], v[84:87]
	v_mfma_f32_16x16x32_bf16 v[80:83], v[182:185], v[206:209], v[80:83]
	v_mfma_f32_16x16x32_bf16 v[68:71], v[148:151], v[214:217], v[68:71]
	v_mfma_f32_16x16x32_bf16 v[64:67], v[182:185], v[214:217], v[64:67]
	s_setprio 0
	s_barrier
	s_add_i32 s22, s52, s40
	v_lshl_add_u64 v[218:219], s[26:27], 0, v[160:161]
	s_mov_b32 m0, s22
	ds_read_b128 v[186:189], v233 offset:16384
	ds_read_b128 v[190:193], v233 offset:17408
	ds_read_b128 v[194:197], v233 offset:18432
	ds_read_b128 v[198:201], v233 offset:19456
	ds_read_b128 v[202:205], v233 offset:20480
	ds_read_b128 v[206:209], v233 offset:21504
	ds_read_b128 v[210:213], v233 offset:22528
	ds_read_b128 v[214:217], v233 offset:23552
	global_load_lds_dwordx4 v[218:219], off
	s_add_i32 m0, s22, 0x2000
	s_add_u32 s22, s26, 0xb0000
	v_lshl_add_u64 v[220:221], s[26:27], 0, v[152:153]
	s_addc_u32 s23, s27, 0
	s_add_i32 s52, s53, s40
	global_load_lds_dwordx4 v[220:221], off
	s_mov_b32 m0, s52
	v_lshl_add_u64 v[234:235], s[28:29], 0, v[154:155]
	global_load_lds_dwordx4 v160, s[22:23]
	s_add_i32 m0, s52, 0x2000
	s_nop 0
	global_load_lds_dwordx4 v152, s[22:23]
	v_lshl_add_u64 v[222:223], s[28:29], 0, v[156:157]
	s_mov_b32 m0, s41
	s_nop 0
	global_load_lds_dwordx4 v[222:223], off
	s_mov_b32 m0, s42
	s_nop 0
	global_load_lds_dwordx4 v[234:235], off
	s_waitcnt vmcnt(8)
	s_waitcnt lgkmcnt(0)
	s_barrier
; #define PG8_STAGE(bufoff, gbase, voff) do { _Pragma("unroll") for (int _i = 0; _i < 2; ++_i) \
;         __builtin_amdgcn_global_load_lds((const unsigned*)((const char*)(gbase) + (voff)[_i]), (PG8_LAS unsigned*)(lds + (bufoff) + ldsw + _i * 8192), 16, 0, 0); } while (0)
; #define PG8_LDA(dst, b, h) do { _Pragma("unroll") for (int m = 0; m < 4; ++m) _Pragma("unroll") for (int k = 0; k < 2; ++k) dst[m][k] = *(const PG8_LAS bf16x8*)(lds + PG8_SA(b, h) + aoff + m * 2048 + k * 1024); } while (0)
; #define PG8_LDB(dst, b, h) do { _Pragma("unroll") for (int n = 0; n < 2; ++n) _Pragma("unroll") for (int k = 0; k < 2; ++k) dst[n][k] = *(const PG8_LAS bf16x8*)(lds + PG8_SB(b, h) + boff + n * 2048 + k * 1024); } while (0)
; #define PG8_MMA(ai, bj, At, Bt) do { __builtin_amdgcn_s_setprio(1); _Pragma("unroll") for (int m = 0; m < 4; ++m) _Pragma("unroll") for (int n = 0; n < 2; ++n) _Pragma("unroll") for (int k = 0; k < 2; ++k) \
;         acc[ai][bj][m][n] = __builtin_amdgcn_mfma_f32_16x16x32_bf16(Bt[n][k], At[m][k], acc[ai][bj][m][n], 0, 0, 0); __builtin_amdgcn_s_setprio(0); } while (0)
; #define PG8_WAIT_V(n) asm volatile("s_waitcnt vmcnt(" #n ")" ::: "memory")
; #define PG8_WAIT_L(n) asm volatile("s_waitcnt lgkmcnt(" #n ")" ::: "memory")
; #define PG8_BAR __builtin_amdgcn_s_barrier()
; #define PG8_SCHED __builtin_amdgcn_sched_barrier(0)
; template <class Epi, class Sched, bool ALIGN_EPI = false, bool SP2 = false>
; __device__ __forceinline__ void gemm_phase(PG8_LAS unsigned char* lds, const Gemm g, const Sched& S, const Epi& E) {
;     ...
;             PG8_WAIT_V(8); PG8_WAIT_L(0); PG8_BAR; PG8_MMA(1, 0, At, B0); PG8_MMA(1, 1, At, B1); PG8_BAR; PG8_SCHED;
;             PG8_LDB(B0, 1, 0); PG8_LDB(B1, 1, 1); PG8_SCHED; PG8_LDA(At, 1, 0); PG8_STAGE(PG8_SA(0, 1), a2 + hstep, voffA);
;             PG8_WAIT_V(8); PG8_WAIT_L(0); PG8_BAR; PG8_MMA(0, 0, At, B0); PG8_MMA(0, 1, At, B1); PG8_BAR; PG8_SCHED;
;             PG8_LDA(At, 1, 1); PG8_STAGE(PG8_SB(1, 0), b3, voffB); PG8_STAGE(PG8_SB(1, 1), b3 + hstep, voffB); PG8_STAGE(PG8_SA(1, 0), a3, voffA);
	s_setprio 1
	s_waitcnt lgkmcnt(0)
	v_mfma_f32_16x16x32_bf16 v[60:63], v[128:131], v[186:189], v[60:63]
	v_mfma_f32_16x16x32_bf16 v[56:59], v[136:139], v[186:189], v[56:59]
	v_mfma_f32_16x16x32_bf16 v[44:47], v[128:131], v[194:197], v[44:47]
	v_mfma_f32_16x16x32_bf16 v[40:43], v[136:139], v[194:197], v[40:43]
	v_mfma_f32_16x16x32_bf16 v[28:31], v[128:131], v[202:205], v[28:31]
	v_mfma_f32_16x16x32_bf16 v[24:27], v[136:139], v[202:205], v[24:27]
	v_mfma_f32_16x16x32_bf16 v[12:15], v[128:131], v[210:213], v[12:15]
	v_mfma_f32_16x16x32_bf16 v[8:11], v[136:139], v[210:213], v[8:11]
	v_mfma_f32_16x16x32_bf16 v[60:63], v[132:135], v[190:193], v[60:63]
	v_mfma_f32_16x16x32_bf16 v[56:59], v[140:143], v[190:193], v[56:59]
	v_mfma_f32_16x16x32_bf16 v[44:47], v[132:135], v[198:201], v[44:47]
	v_mfma_f32_16x16x32_bf16 v[40:43], v[140:143], v[198:201], v[40:43]
	v_mfma_f32_16x16x32_bf16 v[28:31], v[132:135], v[206:209], v[28:31]
	v_mfma_f32_16x16x32_bf16 v[24:27], v[140:143], v[206:209], v[24:27]
	v_mfma_f32_16x16x32_bf16 v[12:15], v[132:135], v[214:217], v[12:15]
	v_mfma_f32_16x16x32_bf16 v[8:11], v[140:143], v[214:217], v[8:11]
	s_setprio 0
	s_setprio 1
	v_mfma_f32_16x16x32_bf16 v[52:55], v[144:147], v[186:189], v[52:55]
	v_mfma_f32_16x16x32_bf16 v[48:51], v[178:181], v[186:189], v[48:51]
	v_mfma_f32_16x16x32_bf16 v[36:39], v[144:147], v[194:197], v[36:39]
	v_mfma_f32_16x16x32_bf16 v[32:35], v[178:181], v[194:197], v[32:35]
	v_mfma_f32_16x16x32_bf16 v[20:23], v[144:147], v[202:205], v[20:23]
	v_mfma_f32_16x16x32_bf16 v[16:19], v[178:181], v[202:205], v[16:19]
	v_mfma_f32_16x16x32_bf16 v[4:7], v[144:147], v[210:213], v[4:7]
	v_mfma_f32_16x16x32_bf16 v[0:3], v[178:181], v[210:213], v[0:3]
	v_mfma_f32_16x16x32_bf16 v[52:55], v[148:151], v[190:193], v[52:55]
	v_mfma_f32_16x16x32_bf16 v[48:51], v[182:185], v[190:193], v[48:51]
	v_mfma_f32_16x16x32_bf16 v[36:39], v[148:151], v[198:201], v[36:39]
	v_mfma_f32_16x16x32_bf16 v[32:35], v[182:185], v[198:201], v[32:35]
	v_mfma_f32_16x16x32_bf16 v[20:23], v[148:151], v[206:209], v[20:23]
	v_mfma_f32_16x16x32_bf16 v[16:19], v[182:185], v[206:209], v[16:19]
	v_mfma_f32_16x16x32_bf16 v[4:7], v[148:151], v[214:217], v[4:7]
	v_mfma_f32_16x16x32_bf16 v[0:3], v[182:185], v[214:217], v[0:3]
	s_setprio 0
	s_barrier
	s_add_i32 s52, 0, 0x18000
	s_add_i32 s53, 0, 0x1c000
	v_add_u32_e32 v140, s52, v175
	v_add_u32_e32 v162, s53, v175
	ds_read_b128 v[128:131], v140
	ds_read_b128 v[132:135], v140 offset:1024
	ds_read_b128 v[136:139], v140 offset:2048
	ds_read_b128 v[140:143], v140 offset:3072
	ds_read_b128 v[144:147], v162
	ds_read_b128 v[148:151], v162 offset:1024
	ds_read_b128 v[178:181], v162 offset:2048
	ds_read_b128 v[182:185], v162 offset:3072
	s_add_u32 s22, s28, 0xb0000
	s_addc_u32 s23, s29, 0
	s_mov_b32 m0, s43
	ds_read_b128 v[186:189], v233 offset:32768
	ds_read_b128 v[190:193], v233 offset:33792
	ds_read_b128 v[194:197], v233 offset:34816
	ds_read_b128 v[198:201], v233 offset:35840
	ds_read_b128 v[202:205], v233 offset:36864
	ds_read_b128 v[206:209], v233 offset:37888
	ds_read_b128 v[210:213], v233 offset:38912
	ds_read_b128 v[214:217], v233 offset:39936
	global_load_lds_dwordx4 v156, s[22:23]
	s_mov_b32 m0, s44
	s_nop 0
	global_load_lds_dwordx4 v154, s[22:23]
	s_waitcnt vmcnt(8)
	s_waitcnt lgkmcnt(0)
	s_barrier
	s_setprio 1
	s_waitcnt lgkmcnt(0)
	v_mfma_f32_16x16x32_bf16 v[124:127], v[128:131], v[186:189], v[124:127]
	v_mfma_f32_16x16x32_bf16 v[120:123], v[136:139], v[186:189], v[120:123]
	v_mfma_f32_16x16x32_bf16 v[108:111], v[128:131], v[194:197], v[108:111]
	v_mfma_f32_16x16x32_bf16 v[104:107], v[136:139], v[194:197], v[104:107]
	v_mfma_f32_16x16x32_bf16 v[92:95], v[128:131], v[202:205], v[92:95]
	v_mfma_f32_16x16x32_bf16 v[88:91], v[136:139], v[202:205], v[88:91]
	v_mfma_f32_16x16x32_bf16 v[76:79], v[128:131], v[210:213], v[76:79]
	v_mfma_f32_16x16x32_bf16 v[72:75], v[136:139], v[210:213], v[72:75]
	v_mfma_f32_16x16x32_bf16 v[124:127], v[132:135], v[190:193], v[124:127]
	v_mfma_f32_16x16x32_bf16 v[120:123], v[140:143], v[190:193], v[120:123]
	v_mfma_f32_16x16x32_bf16 v[108:111], v[132:135], v[198:201], v[108:111]
	v_mfma_f32_16x16x32_bf16 v[104:107], v[140:143], v[198:201], v[104:107]
	v_mfma_f32_16x16x32_bf16 v[92:95], v[132:135], v[206:209], v[92:95]
	v_mfma_f32_16x16x32_bf16 v[88:91], v[140:143], v[206:209], v[88:91]
	v_mfma_f32_16x16x32_bf16 v[76:79], v[132:135], v[214:217], v[76:79]
	v_mfma_f32_16x16x32_bf16 v[72:75], v[140:143], v[214:217], v[72:75]
	s_setprio 0
	s_setprio 1
	v_mfma_f32_16x16x32_bf16 v[116:119], v[144:147], v[186:189], v[116:119]
	v_mfma_f32_16x16x32_bf16 v[112:115], v[178:181], v[186:189], v[112:115]
	v_mfma_f32_16x16x32_bf16 v[100:103], v[144:147], v[194:197], v[100:103]
	v_mfma_f32_16x16x32_bf16 v[96:99], v[178:181], v[194:197], v[96:99]
	v_mfma_f32_16x16x32_bf16 v[84:87], v[144:147], v[202:205], v[84:87]
	v_mfma_f32_16x16x32_bf16 v[80:83], v[178:181], v[202:205], v[80:83]
	v_mfma_f32_16x16x32_bf16 v[68:71], v[144:147], v[210:213], v[68:71]
	v_mfma_f32_16x16x32_bf16 v[64:67], v[178:181], v[210:213], v[64:67]
	v_mfma_f32_16x16x32_bf16 v[116:119], v[148:151], v[190:193], v[116:119]
	v_mfma_f32_16x16x32_bf16 v[112:115], v[182:185], v[190:193], v[112:115]
	v_mfma_f32_16x16x32_bf16 v[100:103], v[148:151], v[198:201], v[100:103]
	v_mfma_f32_16x16x32_bf16 v[96:99], v[182:185], v[198:201], v[96:99]
	v_mfma_f32_16x16x32_bf16 v[84:87], v[148:151], v[206:209], v[84:87]
	v_mfma_f32_16x16x32_bf16 v[80:83], v[182:185], v[206:209], v[80:83]
	v_mfma_f32_16x16x32_bf16 v[68:71], v[148:151], v[214:217], v[68:71]
	v_mfma_f32_16x16x32_bf16 v[64:67], v[182:185], v[214:217], v[64:67]
	s_setprio 0
	s_barrier
; #define PG8_STAGE(bufoff, gbase, voff) do { _Pragma("unroll") for (int _i = 0; _i < 2; ++_i) \
;         __builtin_amdgcn_global_load_lds((const unsigned*)((const char*)(gbase) + (voff)[_i]), (PG8_LAS unsigned*)(lds + (bufoff) + ldsw + _i * 8192), 16, 0, 0); } while (0)
; #define PG8_LDA(dst, b, h) do { _Pragma("unroll") for (int m = 0; m < 4; ++m) _Pragma("unroll") for (int k = 0; k < 2; ++k) dst[m][k] = *(const PG8_LAS bf16x8*)(lds + PG8_SA(b, h) + aoff + m * 2048 + k * 1024); } while (0)
; #define PG8_MMA(ai, bj, At, Bt) do { __builtin_amdgcn_s_setprio(1); _Pragma("unroll") for (int m = 0; m < 4; ++m) _Pragma("unroll") for (int n = 0; n < 2; ++n) _Pragma("unroll") for (int k = 0; k < 2; ++k) \
;         acc[ai][bj][m][n] = __builtin_amdgcn_mfma_f32_16x16x32_bf16(Bt[n][k], At[m][k], acc[ai][bj][m][n], 0, 0, 0); __builtin_amdgcn_s_setprio(0); } while (0)
; #define PG8_WAIT_V(n) asm volatile("s_waitcnt vmcnt(" #n ")" ::: "memory")
; #define PG8_WAIT_L(n) asm volatile("s_waitcnt lgkmcnt(" #n ")" ::: "memory")
; #define PG8_BAR __builtin_amdgcn_s_barrier()
; #define PG8_SCHED __builtin_amdgcn_sched_barrier(0)
; template <class Epi, class Sched, bool ALIGN_EPI = false, bool SP2 = false>
; __device__ __forceinline__ void gemm_phase(PG8_LAS unsigned char* lds, const Gemm g, const Sched& S, const Epi& E) {
;     ...
;             PG8_LDA(At, 1, 1); PG8_STAGE(PG8_SB(1, 0), b3, voffB); PG8_STAGE(PG8_SB(1, 1), b3 + hstep, voffB); PG8_STAGE(PG8_SA(1, 0), a3, voffA);
;             PG8_WAIT_V(8); PG8_WAIT_L(0); PG8_BAR; PG8_MMA(1, 0, At, B0); PG8_MMA(1, 1, At, B1); PG8_BAR; PG8_SCHED;
	s_add_i32 s22, s52, s40
	v_lshl_add_u64 v[218:219], v[218:219], 0, s[50:51]
	s_mov_b32 m0, s22
	ds_read_b128 v[186:189], v233 offset:49152
	ds_read_b128 v[190:193], v233 offset:50176
	ds_read_b128 v[194:197], v233 offset:51200
	ds_read_b128 v[198:201], v233 offset:52224
	ds_read_b128 v[202:205], v233 offset:53248
	ds_read_b128 v[206:209], v233 offset:54272
	ds_read_b128 v[210:213], v233 offset:55296
	ds_read_b128 v[214:217], v233 offset:56320
	global_load_lds_dwordx4 v[218:219], off
	s_add_i32 m0, s22, 0x2000
	s_add_u32 s22, s26, 0xb0080
	v_lshl_add_u64 v[218:219], v[220:221], 0, s[50:51]
	s_addc_u32 s23, s27, 0
	s_add_i32 s26, s53, s40
	global_load_lds_dwordx4 v[218:219], off
	s_mov_b32 m0, s26
	s_nop 0
	global_load_lds_dwordx4 v160, s[22:23]
	s_add_i32 m0, s26, 0x2000
	s_nop 0
	global_load_lds_dwordx4 v152, s[22:23]
	v_lshl_add_u64 v[218:219], v[222:223], 0, s[50:51]
	s_mov_b32 m0, s46
	s_nop 0
	global_load_lds_dwordx4 v[218:219], off
	v_lshl_add_u64 v[218:219], v[234:235], 0, s[50:51]
	s_mov_b32 m0, s47
	s_nop 0
	global_load_lds_dwordx4 v[218:219], off
	s_waitcnt vmcnt(8)
	s_waitcnt lgkmcnt(0)
	s_barrier
	s_setprio 1
	s_waitcnt lgkmcnt(0)
	v_mfma_f32_16x16x32_bf16 v[60:63], v[128:131], v[186:189], v[60:63]
	v_mfma_f32_16x16x32_bf16 v[56:59], v[136:139], v[186:189], v[56:59]
	v_mfma_f32_16x16x32_bf16 v[44:47], v[128:131], v[194:197], v[44:47]
	v_mfma_f32_16x16x32_bf16 v[40:43], v[136:139], v[194:197], v[40:43]
	v_mfma_f32_16x16x32_bf16 v[28:31], v[128:131], v[202:205], v[28:31]
	v_mfma_f32_16x16x32_bf16 v[24:27], v[136:139], v[202:205], v[24:27]
	v_mfma_f32_16x16x32_bf16 v[12:15], v[128:131], v[210:213], v[12:15]
	v_mfma_f32_16x16x32_bf16 v[8:11], v[136:139], v[210:213], v[8:11]
	v_mfma_f32_16x16x32_bf16 v[60:63], v[132:135], v[190:193], v[60:63]
	v_mfma_f32_16x16x32_bf16 v[56:59], v[140:143], v[190:193], v[56:59]
	v_mfma_f32_16x16x32_bf16 v[44:47], v[132:135], v[198:201], v[44:47]
	v_mfma_f32_16x16x32_bf16 v[40:43], v[140:143], v[198:201], v[40:43]
	v_mfma_f32_16x16x32_bf16 v[28:31], v[132:135], v[206:209], v[28:31]
	v_mfma_f32_16x16x32_bf16 v[24:27], v[140:143], v[206:209], v[24:27]
	v_mfma_f32_16x16x32_bf16 v[12:15], v[132:135], v[214:217], v[12:15]
	v_mfma_f32_16x16x32_bf16 v[8:11], v[140:143], v[214:217], v[8:11]
	s_setprio 0
	s_setprio 1
	v_mfma_f32_16x16x32_bf16 v[52:55], v[144:147], v[186:189], v[52:55]
	v_mfma_f32_16x16x32_bf16 v[48:51], v[178:181], v[186:189], v[48:51]
	v_mfma_f32_16x16x32_bf16 v[36:39], v[144:147], v[194:197], v[36:39]
	v_mfma_f32_16x16x32_bf16 v[32:35], v[178:181], v[194:197], v[32:35]
	v_mfma_f32_16x16x32_bf16 v[20:23], v[144:147], v[202:205], v[20:23]
	v_mfma_f32_16x16x32_bf16 v[16:19], v[178:181], v[202:205], v[16:19]
	v_mfma_f32_16x16x32_bf16 v[4:7], v[144:147], v[210:213], v[4:7]
	v_mfma_f32_16x16x32_bf16 v[0:3], v[178:181], v[210:213], v[0:3]
	v_mfma_f32_16x16x32_bf16 v[52:55], v[148:151], v[190:193], v[52:55]
	v_mfma_f32_16x16x32_bf16 v[48:51], v[182:185], v[190:193], v[48:51]
	v_mfma_f32_16x16x32_bf16 v[36:39], v[148:151], v[198:201], v[36:39]
	v_mfma_f32_16x16x32_bf16 v[32:35], v[182:185], v[198:201], v[32:35]
	v_mfma_f32_16x16x32_bf16 v[20:23], v[148:151], v[206:209], v[20:23]
	v_mfma_f32_16x16x32_bf16 v[16:19], v[182:185], v[206:209], v[16:19]
	v_mfma_f32_16x16x32_bf16 v[4:7], v[148:151], v[214:217], v[4:7]
	v_mfma_f32_16x16x32_bf16 v[0:3], v[182:185], v[214:217], v[0:3]
	s_setprio 0
	s_barrier
	s_add_i32 s68, s68, 2
	s_add_u32 vcc_lo, vcc_lo, 0x100
	s_addc_u32 vcc_hi, vcc_hi, 0
	s_cmp_gt_u32 s68, 41
	s_mov_b64 s[22:23], s[24:25]
	s_cbranch_scc0 .LBB0_177
	s_and_b64 vcc, exec, s[18:19]
	s_cbranch_vccz .LBB0_180
	s_barrier

; #define PG8_STAGE(bufoff, gbase, voff) do { _Pragma("unroll") for (int _i = 0; _i < 2; ++_i) \
;         __builtin_amdgcn_global_load_lds((const unsigned*)((const char*)(gbase) + (voff)[_i]), (PG8_LAS unsigned*)(lds + (bufoff) + ldsw + _i * 8192), 16, 0, 0); } while (0)
; #define PG8_LDA(dst, b, h) do { _Pragma("unroll") for (int m = 0; m < 4; ++m) _Pragma("unroll") for (int k = 0; k < 2; ++k) dst[m][k] = *(const PG8_LAS bf16x8*)(lds + PG8_SA(b, h) + aoff + m * 2048 + k * 1024); } while (0)
; #define PG8_LDB(dst, b, h) do { _Pragma("unroll") for (int n = 0; n < 2; ++n) _Pragma("unroll") for (int k = 0; k < 2; ++k) dst[n][k] = *(const PG8_LAS bf16x8*)(lds + PG8_SB(b, h) + boff + n * 2048 + k * 1024); } while (0)
; #define PG8_MMA(ai, bj, At, Bt) do { __builtin_amdgcn_s_setprio(1); _Pragma("unroll") for (int m = 0; m < 4; ++m) _Pragma("unroll") for (int n = 0; n < 2; ++n) _Pragma("unroll") for (int k = 0; k < 2; ++k) \
;         acc[ai][bj][m][n] = __builtin_amdgcn_mfma_f32_16x16x32_bf16(Bt[n][k], At[m][k], acc[ai][bj][m][n], 0, 0, 0); __builtin_amdgcn_s_setprio(0); } while (0)
; #define PG8_WAIT_V(n) asm volatile("s_waitcnt vmcnt(" #n ")" ::: "memory")
; #define PG8_WAIT_L(n) asm volatile("s_waitcnt lgkmcnt(" #n ")" ::: "memory")
; #define PG8_BAR __builtin_amdgcn_s_barrier()
; #define PG8_SCHED __builtin_amdgcn_sched_barrier(0)
; template <class Epi, class Sched, bool ALIGN_EPI = false, bool SP2 = false>
; __device__ __forceinline__ void gemm_phase(PG8_LAS unsigned char* lds, const Gemm g, const Sched& S, const Epi& E) {
;     ...
;             PG8_LDB(B0, 0, 0); PG8_LDB(B1, 0, 1); PG8_SCHED; PG8_LDA(At, 0, 0); PG8_STAGE(PG8_SA(1, 1), a1 + hstep, voffA);
;             PG8_WAIT_V(8); PG8_WAIT_L(0); PG8_BAR; PG8_MMA(0, 0, At, B0); PG8_MMA(0, 1, At, B1); PG8_BAR; PG8_SCHED;
;             PG8_LDA(At, 0, 1); PG8_STAGE(PG8_SB(0, 0), b2, voffB); PG8_STAGE(PG8_SB(0, 1), b2 + hstep, voffB); PG8_STAGE(PG8_SA(0, 0), a2, voffA);
;             PG8_WAIT_V(8); PG8_WAIT_L(0); PG8_BAR; PG8_MMA(1, 0, At, B0); PG8_MMA(1, 1, At, B1); PG8_BAR; PG8_SCHED;
.LBB0_270:
	s_add_u32 s8, s6, 0xfffc0080
	s_addc_u32 s9, s7, -1
	s_add_i32 s52, 0, 0x10000
	s_cmp_eq_u32 s86, 12
	s_cselect_b32 s25, s19, s9
	s_cselect_b32 s24, s47, s8
	s_cselect_b32 s9, s17, s76
	s_cselect_b32 s8, s64, s65
	s_add_i32 s53, 0, 0x14000
	v_add_u32_e32 v140, s52, v175
	v_add_u32_e32 v156, s53, v175
	ds_read_b128 v[128:131], v140
	ds_read_b128 v[132:135], v140 offset:1024
	ds_read_b128 v[136:139], v140 offset:2048
	ds_read_b128 v[140:143], v140 offset:3072
	ds_read_b128 v[144:147], v156
	ds_read_b128 v[148:151], v156 offset:1024
	ds_read_b128 v[152:155], v156 offset:2048
	ds_read_b128 v[156:159], v156 offset:3072
	s_add_i32 m0, s34, 0xc000
	ds_read_b128 v[190:193], v214
	ds_read_b128 v[194:197], v214 offset:1024
	ds_read_b128 v[198:201], v214 offset:2048
	ds_read_b128 v[202:205], v214 offset:3072
	ds_read_b128 v[206:209], v214 offset:4096
	ds_read_b128 v[216:219], v214 offset:5120
	ds_read_b128 v[220:223], v214 offset:6144
	ds_read_b128 v[232:235], v214 offset:7168
	global_load_lds_dwordx4 v186, s[6:7]
	s_add_i32 m0, s34, 0xe000
	s_nop 0
	global_load_lds_dwordx4 v188, s[6:7]
	s_waitcnt vmcnt(8)
	s_waitcnt lgkmcnt(0)
	s_barrier
	s_setprio 1
	s_waitcnt lgkmcnt(0)
	v_mfma_f32_16x16x32_bf16 v[124:127], v[128:131], v[190:193], v[124:127]
	v_mfma_f32_16x16x32_bf16 v[120:123], v[136:139], v[190:193], v[120:123]
	v_mfma_f32_16x16x32_bf16 v[108:111], v[128:131], v[198:201], v[108:111]
	v_mfma_f32_16x16x32_bf16 v[104:107], v[136:139], v[198:201], v[104:107]
	v_mfma_f32_16x16x32_bf16 v[92:95], v[128:131], v[206:209], v[92:95]
	v_mfma_f32_16x16x32_bf16 v[88:91], v[136:139], v[206:209], v[88:91]
	v_mfma_f32_16x16x32_bf16 v[76:79], v[128:131], v[220:223], v[76:79]
	v_mfma_f32_16x16x32_bf16 v[72:75], v[136:139], v[220:223], v[72:75]
	v_mfma_f32_16x16x32_bf16 v[124:127], v[132:135], v[194:197], v[124:127]
	v_mfma_f32_16x16x32_bf16 v[120:123], v[140:143], v[194:197], v[120:123]
	v_mfma_f32_16x16x32_bf16 v[108:111], v[132:135], v[202:205], v[108:111]
	v_mfma_f32_16x16x32_bf16 v[104:107], v[140:143], v[202:205], v[104:107]
	v_mfma_f32_16x16x32_bf16 v[92:95], v[132:135], v[216:219], v[92:95]
	v_mfma_f32_16x16x32_bf16 v[88:91], v[140:143], v[216:219], v[88:91]
	v_mfma_f32_16x16x32_bf16 v[76:79], v[132:135], v[232:235], v[76:79]
	v_mfma_f32_16x16x32_bf16 v[72:75], v[140:143], v[232:235], v[72:75]
	s_setprio 0
	s_setprio 1
	v_mfma_f32_16x16x32_bf16 v[116:119], v[144:147], v[190:193], v[116:119]
	v_mfma_f32_16x16x32_bf16 v[112:115], v[152:155], v[190:193], v[112:115]
	v_mfma_f32_16x16x32_bf16 v[100:103], v[144:147], v[198:201], v[100:103]
	v_mfma_f32_16x16x32_bf16 v[96:99], v[152:155], v[198:201], v[96:99]
	v_mfma_f32_16x16x32_bf16 v[84:87], v[144:147], v[206:209], v[84:87]
	v_mfma_f32_16x16x32_bf16 v[80:83], v[152:155], v[206:209], v[80:83]
	v_mfma_f32_16x16x32_bf16 v[68:71], v[144:147], v[220:223], v[68:71]
	v_mfma_f32_16x16x32_bf16 v[64:67], v[152:155], v[220:223], v[64:67]
	v_mfma_f32_16x16x32_bf16 v[116:119], v[148:151], v[194:197], v[116:119]
	v_mfma_f32_16x16x32_bf16 v[112:115], v[156:159], v[194:197], v[112:115]
	v_mfma_f32_16x16x32_bf16 v[100:103], v[148:151], v[202:205], v[100:103]
	v_mfma_f32_16x16x32_bf16 v[96:99], v[156:159], v[202:205], v[96:99]
	v_mfma_f32_16x16x32_bf16 v[84:87], v[148:151], v[216:219], v[84:87]
	v_mfma_f32_16x16x32_bf16 v[80:83], v[156:159], v[216:219], v[80:83]
	v_mfma_f32_16x16x32_bf16 v[68:71], v[148:151], v[232:235], v[68:71]
	v_mfma_f32_16x16x32_bf16 v[64:67], v[156:159], v[232:235], v[64:67]
	s_setprio 0
	s_barrier
	s_add_i32 s52, s52, s26
	v_lshl_add_u64 v[162:163], s[8:9], 0, v[160:161]
	s_mov_b32 m0, s52
	ds_read_b128 v[190:193], v214 offset:16384
	ds_read_b128 v[194:197], v214 offset:17408
	ds_read_b128 v[198:201], v214 offset:18432
	ds_read_b128 v[202:205], v214 offset:19456
	ds_read_b128 v[206:209], v214 offset:20480
	ds_read_b128 v[216:219], v214 offset:21504
	ds_read_b128 v[220:223], v214 offset:22528
	ds_read_b128 v[232:235], v214 offset:23552
	global_load_lds_dwordx4 v[162:163], off
	s_add_i32 m0, s52, 0x2000
	s_add_u32 s68, s8, 0x40000
	v_lshl_add_u64 v[164:165], s[8:9], 0, v[176:177]
	s_addc_u32 s69, s9, 0
	s_add_i32 s52, s53, s26
	global_load_lds_dwordx4 v[164:165], off
	s_mov_b32 m0, s52
	v_lshl_add_u64 v[226:227], s[24:25], 0, v[178:179]
	global_load_lds_dwordx4 v160, s[68:69]
	s_add_i32 m0, s52, 0x2000
	s_nop 0
	global_load_lds_dwordx4 v176, s[68:69]
	v_lshl_add_u64 v[210:211], s[24:25], 0, v[180:181]
	s_mov_b32 m0, s34
	s_nop 0
	global_load_lds_dwordx4 v[210:211], off
	s_mov_b32 m0, s35
	s_nop 0
	global_load_lds_dwordx4 v[226:227], off
	s_waitcnt vmcnt(8)
	s_waitcnt lgkmcnt(0)
	s_barrier
; #define PG8_STAGE(bufoff, gbase, voff) do { _Pragma("unroll") for (int _i = 0; _i < 2; ++_i) \
;         __builtin_amdgcn_global_load_lds((const unsigned*)((const char*)(gbase) + (voff)[_i]), (PG8_LAS unsigned*)(lds + (bufoff) + ldsw + _i * 8192), 16, 0, 0); } while (0)
; #define PG8_LDA(dst, b, h) do { _Pragma("unroll") for (int m = 0; m < 4; ++m) _Pragma("unroll") for (int k = 0; k < 2; ++k) dst[m][k] = *(const PG8_LAS bf16x8*)(lds + PG8_SA(b, h) + aoff + m * 2048 + k * 1024); } while (0)
; #define PG8_LDB(dst, b, h) do { _Pragma("unroll") for (int n = 0; n < 2; ++n) _Pragma("unroll") for (int k = 0; k < 2; ++k) dst[n][k] = *(const PG8_LAS bf16x8*)(lds + PG8_SB(b, h) + boff + n * 2048 + k * 1024); } while (0)
; #define PG8_MMA(ai, bj, At, Bt) do { __builtin_amdgcn_s_setprio(1); _Pragma("unroll") for (int m = 0; m < 4; ++m) _Pragma("unroll") for (int n = 0; n < 2; ++n) _Pragma("unroll") for (int k = 0; k < 2; ++k) \
;         acc[ai][bj][m][n] = __builtin_amdgcn_mfma_f32_16x16x32_bf16(Bt[n][k], At[m][k], acc[ai][bj][m][n], 0, 0, 0); __builtin_amdgcn_s_setprio(0); } while (0)
; #define PG8_WAIT_V(n) asm volatile("s_waitcnt vmcnt(" #n ")" ::: "memory")
; #define PG8_WAIT_L(n) asm volatile("s_waitcnt lgkmcnt(" #n ")" ::: "memory")
; #define PG8_BAR __builtin_amdgcn_s_barrier()
; #define PG8_SCHED __builtin_amdgcn_sched_barrier(0)
; template <class Epi, class Sched, bool ALIGN_EPI = false, bool SP2 = false>
; __device__ __forceinline__ void gemm_phase(PG8_LAS unsigned char* lds, const Gemm g, const Sched& S, const Epi& E) {
;     ...
;             PG8_WAIT_V(8); PG8_WAIT_L(0); PG8_BAR; PG8_MMA(1, 0, At, B0); PG8_MMA(1, 1, At, B1); PG8_BAR; PG8_SCHED;
;             PG8_LDB(B0, 1, 0); PG8_LDB(B1, 1, 1); PG8_SCHED; PG8_LDA(At, 1, 0); PG8_STAGE(PG8_SA(0, 1), a2 + hstep, voffA);
;             PG8_WAIT_V(8); PG8_WAIT_L(0); PG8_BAR; PG8_MMA(0, 0, At, B0); PG8_MMA(0, 1, At, B1); PG8_BAR; PG8_SCHED;
;             PG8_LDA(At, 1, 1); PG8_STAGE(PG8_SB(1, 0), b3, voffB); PG8_STAGE(PG8_SB(1, 1), b3 + hstep, voffB); PG8_STAGE(PG8_SA(1, 0), a3, voffA);
	s_setprio 1
	s_waitcnt lgkmcnt(0)
	v_mfma_f32_16x16x32_bf16 v[60:63], v[128:131], v[190:193], v[60:63]
	v_mfma_f32_16x16x32_bf16 v[56:59], v[136:139], v[190:193], v[56:59]
	v_mfma_f32_16x16x32_bf16 v[44:47], v[128:131], v[198:201], v[44:47]
	v_mfma_f32_16x16x32_bf16 v[40:43], v[136:139], v[198:201], v[40:43]
	v_mfma_f32_16x16x32_bf16 v[28:31], v[128:131], v[206:209], v[28:31]
	v_mfma_f32_16x16x32_bf16 v[24:27], v[136:139], v[206:209], v[24:27]
	v_mfma_f32_16x16x32_bf16 v[12:15], v[128:131], v[220:223], v[12:15]
	v_mfma_f32_16x16x32_bf16 v[8:11], v[136:139], v[220:223], v[8:11]
	v_mfma_f32_16x16x32_bf16 v[60:63], v[132:135], v[194:197], v[60:63]
	v_mfma_f32_16x16x32_bf16 v[56:59], v[140:143], v[194:197], v[56:59]
	v_mfma_f32_16x16x32_bf16 v[44:47], v[132:135], v[202:205], v[44:47]
	v_mfma_f32_16x16x32_bf16 v[40:43], v[140:143], v[202:205], v[40:43]
	v_mfma_f32_16x16x32_bf16 v[28:31], v[132:135], v[216:219], v[28:31]
	v_mfma_f32_16x16x32_bf16 v[24:27], v[140:143], v[216:219], v[24:27]
	v_mfma_f32_16x16x32_bf16 v[12:15], v[132:135], v[232:235], v[12:15]
	v_mfma_f32_16x16x32_bf16 v[8:11], v[140:143], v[232:235], v[8:11]
	s_setprio 0
	s_setprio 1
	v_mfma_f32_16x16x32_bf16 v[52:55], v[144:147], v[190:193], v[52:55]
	v_mfma_f32_16x16x32_bf16 v[48:51], v[152:155], v[190:193], v[48:51]
	v_mfma_f32_16x16x32_bf16 v[36:39], v[144:147], v[198:201], v[36:39]
	v_mfma_f32_16x16x32_bf16 v[32:35], v[152:155], v[198:201], v[32:35]
	v_mfma_f32_16x16x32_bf16 v[20:23], v[144:147], v[206:209], v[20:23]
	v_mfma_f32_16x16x32_bf16 v[16:19], v[152:155], v[206:209], v[16:19]
	v_mfma_f32_16x16x32_bf16 v[4:7], v[144:147], v[220:223], v[4:7]
	v_mfma_f32_16x16x32_bf16 v[0:3], v[152:155], v[220:223], v[0:3]
	v_mfma_f32_16x16x32_bf16 v[52:55], v[148:151], v[194:197], v[52:55]
	v_mfma_f32_16x16x32_bf16 v[48:51], v[156:159], v[194:197], v[48:51]
	v_mfma_f32_16x16x32_bf16 v[36:39], v[148:151], v[202:205], v[36:39]
	v_mfma_f32_16x16x32_bf16 v[32:35], v[156:159], v[202:205], v[32:35]
	v_mfma_f32_16x16x32_bf16 v[20:23], v[148:151], v[216:219], v[20:23]
	v_mfma_f32_16x16x32_bf16 v[16:19], v[156:159], v[216:219], v[16:19]
	v_mfma_f32_16x16x32_bf16 v[4:7], v[148:151], v[232:235], v[4:7]
	v_mfma_f32_16x16x32_bf16 v[0:3], v[156:159], v[232:235], v[0:3]
	s_setprio 0
	s_barrier
	s_add_i32 s52, 0, 0x18000
	s_add_i32 s53, 0, 0x1c000
	v_add_u32_e32 v140, s52, v175
	v_add_u32_e32 v156, s53, v175
	ds_read_b128 v[128:131], v140
	ds_read_b128 v[132:135], v140 offset:1024
	ds_read_b128 v[136:139], v140 offset:2048
	ds_read_b128 v[140:143], v140 offset:3072
	ds_read_b128 v[144:147], v156
	ds_read_b128 v[148:151], v156 offset:1024
	ds_read_b128 v[152:155], v156 offset:2048
	ds_read_b128 v[156:159], v156 offset:3072
	s_add_u32 s24, s24, 0x40000
	s_addc_u32 s25, s25, 0
	s_mov_b32 m0, s40
	ds_read_b128 v[190:193], v214 offset:32768
	ds_read_b128 v[194:197], v214 offset:33792
	ds_read_b128 v[198:201], v214 offset:34816
	ds_read_b128 v[202:205], v214 offset:35840
	ds_read_b128 v[206:209], v214 offset:36864
	ds_read_b128 v[216:219], v214 offset:37888
	ds_read_b128 v[220:223], v214 offset:38912
	ds_read_b128 v[232:235], v214 offset:39936
	global_load_lds_dwordx4 v180, s[24:25]
	s_mov_b32 m0, s41
	s_nop 0
	global_load_lds_dwordx4 v178, s[24:25]
	s_waitcnt vmcnt(8)
	s_waitcnt lgkmcnt(0)
	s_barrier
	s_setprio 1
	s_waitcnt lgkmcnt(0)
	v_mfma_f32_16x16x32_bf16 v[124:127], v[128:131], v[190:193], v[124:127]
	v_mfma_f32_16x16x32_bf16 v[120:123], v[136:139], v[190:193], v[120:123]
	v_mfma_f32_16x16x32_bf16 v[108:111], v[128:131], v[198:201], v[108:111]
	v_mfma_f32_16x16x32_bf16 v[104:107], v[136:139], v[198:201], v[104:107]
	v_mfma_f32_16x16x32_bf16 v[92:95], v[128:131], v[206:209], v[92:95]
	v_mfma_f32_16x16x32_bf16 v[88:91], v[136:139], v[206:209], v[88:91]
	v_mfma_f32_16x16x32_bf16 v[76:79], v[128:131], v[220:223], v[76:79]
	v_mfma_f32_16x16x32_bf16 v[72:75], v[136:139], v[220:223], v[72:75]
	v_mfma_f32_16x16x32_bf16 v[124:127], v[132:135], v[194:197], v[124:127]
	v_mfma_f32_16x16x32_bf16 v[120:123], v[140:143], v[194:197], v[120:123]
	v_mfma_f32_16x16x32_bf16 v[108:111], v[132:135], v[202:205], v[108:111]
	v_mfma_f32_16x16x32_bf16 v[104:107], v[140:143], v[202:205], v[104:107]
	v_mfma_f32_16x16x32_bf16 v[92:95], v[132:135], v[216:219], v[92:95]
	v_mfma_f32_16x16x32_bf16 v[88:91], v[140:143], v[216:219], v[88:91]
	v_mfma_f32_16x16x32_bf16 v[76:79], v[132:135], v[232:235], v[76:79]
	v_mfma_f32_16x16x32_bf16 v[72:75], v[140:143], v[232:235], v[72:75]
	s_setprio 0
	s_setprio 1
	v_mfma_f32_16x16x32_bf16 v[116:119], v[144:147], v[190:193], v[116:119]
	v_mfma_f32_16x16x32_bf16 v[112:115], v[152:155], v[190:193], v[112:115]
	v_mfma_f32_16x16x32_bf16 v[100:103], v[144:147], v[198:201], v[100:103]
	v_mfma_f32_16x16x32_bf16 v[96:99], v[152:155], v[198:201], v[96:99]
	v_mfma_f32_16x16x32_bf16 v[84:87], v[144:147], v[206:209], v[84:87]
	v_mfma_f32_16x16x32_bf16 v[80:83], v[152:155], v[206:209], v[80:83]
	v_mfma_f32_16x16x32_bf16 v[68:71], v[144:147], v[220:223], v[68:71]
	v_mfma_f32_16x16x32_bf16 v[64:67], v[152:155], v[220:223], v[64:67]
	v_mfma_f32_16x16x32_bf16 v[116:119], v[148:151], v[194:197], v[116:119]
	v_mfma_f32_16x16x32_bf16 v[112:115], v[156:159], v[194:197], v[112:115]
	v_mfma_f32_16x16x32_bf16 v[100:103], v[148:151], v[202:205], v[100:103]
	v_mfma_f32_16x16x32_bf16 v[96:99], v[156:159], v[202:205], v[96:99]
	v_mfma_f32_16x16x32_bf16 v[84:87], v[148:151], v[216:219], v[84:87]
	v_mfma_f32_16x16x32_bf16 v[80:83], v[156:159], v[216:219], v[80:83]
	v_mfma_f32_16x16x32_bf16 v[68:71], v[148:151], v[232:235], v[68:71]
	v_mfma_f32_16x16x32_bf16 v[64:67], v[156:159], v[232:235], v[64:67]
	s_setprio 0
	s_barrier
; #define PG8_STAGE(bufoff, gbase, voff) do { _Pragma("unroll") for (int _i = 0; _i < 2; ++_i) \
;         __builtin_amdgcn_global_load_lds((const unsigned*)((const char*)(gbase) + (voff)[_i]), (PG8_LAS unsigned*)(lds + (bufoff) + ldsw + _i * 8192), 16, 0, 0); } while (0)
; #define PG8_LDA(dst, b, h) do { _Pragma("unroll") for (int m = 0; m < 4; ++m) _Pragma("unroll") for (int k = 0; k < 2; ++k) dst[m][k] = *(const PG8_LAS bf16x8*)(lds + PG8_SA(b, h) + aoff + m * 2048 + k * 1024); } while (0)
; #define PG8_MMA(ai, bj, At, Bt) do { __builtin_amdgcn_s_setprio(1); _Pragma("unroll") for (int m = 0; m < 4; ++m) _Pragma("unroll") for (int n = 0; n < 2; ++n) _Pragma("unroll") for (int k = 0; k < 2; ++k) \
;         acc[ai][bj][m][n] = __builtin_amdgcn_mfma_f32_16x16x32_bf16(Bt[n][k], At[m][k], acc[ai][bj][m][n], 0, 0, 0); __builtin_amdgcn_s_setprio(0); } while (0)
; #define PG8_WAIT_V(n) asm volatile("s_waitcnt vmcnt(" #n ")" ::: "memory")
; #define PG8_WAIT_L(n) asm volatile("s_waitcnt lgkmcnt(" #n ")" ::: "memory")
; #define PG8_BAR __builtin_amdgcn_s_barrier()
; #define PG8_SCHED __builtin_amdgcn_sched_barrier(0)
; template <class Epi, class Sched, bool ALIGN_EPI = false, bool SP2 = false>
; __device__ __forceinline__ void gemm_phase(PG8_LAS unsigned char* lds, const Gemm g, const Sched& S, const Epi& E) {
;     ...
;             PG8_LDA(At, 1, 1); PG8_STAGE(PG8_SB(1, 0), b3, voffB); PG8_STAGE(PG8_SB(1, 1), b3 + hstep, voffB); PG8_STAGE(PG8_SA(1, 0), a3, voffA);
;             PG8_WAIT_V(8); PG8_WAIT_L(0); PG8_BAR; PG8_MMA(1, 0, At, B0); PG8_MMA(1, 1, At, B1); PG8_BAR; PG8_SCHED;
	s_add_i32 s24, s52, s26
	v_lshl_add_u64 v[162:163], v[162:163], 0, s[50:51]
	s_mov_b32 m0, s24
	ds_read_b128 v[190:193], v214 offset:49152
	ds_read_b128 v[194:197], v214 offset:50176
	ds_read_b128 v[198:201], v214 offset:51200
	ds_read_b128 v[202:205], v214 offset:52224
	ds_read_b128 v[206:209], v214 offset:53248
	ds_read_b128 v[216:219], v214 offset:54272
	ds_read_b128 v[220:223], v214 offset:55296
	ds_read_b128 v[232:235], v214 offset:56320
	global_load_lds_dwordx4 v[162:163], off
	s_add_i32 m0, s24, 0x2000
	s_add_u32 s8, s8, 0x40080
	v_lshl_add_u64 v[162:163], v[164:165], 0, s[50:51]
	s_addc_u32 s9, s9, 0
	s_add_i32 s24, s53, s26
	global_load_lds_dwordx4 v[162:163], off
	s_mov_b32 m0, s24
	s_nop 0
	global_load_lds_dwordx4 v160, s[8:9]
	s_add_i32 m0, s24, 0x2000
	s_nop 0
	global_load_lds_dwordx4 v176, s[8:9]
	v_lshl_add_u64 v[162:163], v[210:211], 0, s[50:51]
	s_mov_b32 m0, s42
	s_nop 0
	global_load_lds_dwordx4 v[162:163], off
	v_lshl_add_u64 v[162:163], v[226:227], 0, s[50:51]
	s_mov_b32 m0, s43
	s_nop 0
	global_load_lds_dwordx4 v[162:163], off
	s_waitcnt vmcnt(8)
	s_waitcnt lgkmcnt(0)
	s_barrier
	s_setprio 1
	s_waitcnt lgkmcnt(0)
	v_mfma_f32_16x16x32_bf16 v[60:63], v[128:131], v[190:193], v[60:63]
	v_mfma_f32_16x16x32_bf16 v[56:59], v[136:139], v[190:193], v[56:59]
	v_mfma_f32_16x16x32_bf16 v[44:47], v[128:131], v[198:201], v[44:47]
	v_mfma_f32_16x16x32_bf16 v[40:43], v[136:139], v[198:201], v[40:43]
	v_mfma_f32_16x16x32_bf16 v[28:31], v[128:131], v[206:209], v[28:31]
	v_mfma_f32_16x16x32_bf16 v[24:27], v[136:139], v[206:209], v[24:27]
	v_mfma_f32_16x16x32_bf16 v[12:15], v[128:131], v[220:223], v[12:15]
	v_mfma_f32_16x16x32_bf16 v[8:11], v[136:139], v[220:223], v[8:11]
	v_mfma_f32_16x16x32_bf16 v[60:63], v[132:135], v[194:197], v[60:63]
	v_mfma_f32_16x16x32_bf16 v[56:59], v[140:143], v[194:197], v[56:59]
	v_mfma_f32_16x16x32_bf16 v[44:47], v[132:135], v[202:205], v[44:47]
	v_mfma_f32_16x16x32_bf16 v[40:43], v[140:143], v[202:205], v[40:43]
	v_mfma_f32_16x16x32_bf16 v[28:31], v[132:135], v[216:219], v[28:31]
	v_mfma_f32_16x16x32_bf16 v[24:27], v[140:143], v[216:219], v[24:27]
	v_mfma_f32_16x16x32_bf16 v[12:15], v[132:135], v[232:235], v[12:15]
	v_mfma_f32_16x16x32_bf16 v[8:11], v[140:143], v[232:235], v[8:11]
	s_setprio 0
	s_setprio 1
	v_mfma_f32_16x16x32_bf16 v[52:55], v[144:147], v[190:193], v[52:55]
	v_mfma_f32_16x16x32_bf16 v[48:51], v[152:155], v[190:193], v[48:51]
	v_mfma_f32_16x16x32_bf16 v[36:39], v[144:147], v[198:201], v[36:39]
	v_mfma_f32_16x16x32_bf16 v[32:35], v[152:155], v[198:201], v[32:35]
	v_mfma_f32_16x16x32_bf16 v[20:23], v[144:147], v[206:209], v[20:23]
	v_mfma_f32_16x16x32_bf16 v[16:19], v[152:155], v[206:209], v[16:19]
	v_mfma_f32_16x16x32_bf16 v[4:7], v[144:147], v[220:223], v[4:7]
	v_mfma_f32_16x16x32_bf16 v[0:3], v[152:155], v[220:223], v[0:3]
	v_mfma_f32_16x16x32_bf16 v[52:55], v[148:151], v[194:197], v[52:55]
	v_mfma_f32_16x16x32_bf16 v[48:51], v[156:159], v[194:197], v[48:51]
	v_mfma_f32_16x16x32_bf16 v[36:39], v[148:151], v[202:205], v[36:39]
	v_mfma_f32_16x16x32_bf16 v[32:35], v[156:159], v[202:205], v[32:35]
	v_mfma_f32_16x16x32_bf16 v[20:23], v[148:151], v[216:219], v[20:23]
	v_mfma_f32_16x16x32_bf16 v[16:19], v[156:159], v[216:219], v[16:19]
	v_mfma_f32_16x16x32_bf16 v[4:7], v[148:151], v[232:235], v[4:7]
	v_mfma_f32_16x16x32_bf16 v[0:3], v[156:159], v[232:235], v[0:3]
	s_setprio 0
	s_barrier
	s_add_i32 s86, s86, 2
	s_add_u32 s6, s6, 0x100
	s_addc_u32 s7, s7, 0
	s_add_u32 s65, s65, 0x100
	s_addc_u32 s76, s76, 0
	s_cmp_gt_u32 s86, 13
	s_cbranch_scc0 .LBB0_270
	s_and_b64 vcc, exec, s[14:15]
	s_cbranch_vccz .LBB0_273
	s_barrier

; #define PG8_STAGE(bufoff, gbase, voff) do { _Pragma("unroll") for (int _i = 0; _i < 2; ++_i) \
;         __builtin_amdgcn_global_load_lds((const unsigned*)((const char*)(gbase) + (voff)[_i]), (PG8_LAS unsigned*)(lds + (bufoff) + ldsw + _i * 8192), 16, 0, 0); } while (0)
; #define PG8_LDA(dst, b, h) do { _Pragma("unroll") for (int m = 0; m < 4; ++m) _Pragma("unroll") for (int k = 0; k < 2; ++k) dst[m][k] = *(const PG8_LAS bf16x8*)(lds + PG8_SA(b, h) + aoff + m * 2048 + k * 1024); } while (0)
; #define PG8_LDB(dst, b, h) do { _Pragma("unroll") for (int n = 0; n < 2; ++n) _Pragma("unroll") for (int k = 0; k < 2; ++k) dst[n][k] = *(const PG8_LAS bf16x8*)(lds + PG8_SB(b, h) + boff + n * 2048 + k * 1024); } while (0)
; #define PG8_MMA(ai, bj, At, Bt) do { __builtin_amdgcn_s_setprio(1); _Pragma("unroll") for (int m = 0; m < 4; ++m) _Pragma("unroll") for (int n = 0; n < 2; ++n) _Pragma("unroll") for (int k = 0; k < 2; ++k) \
;         acc[ai][bj][m][n] = __builtin_amdgcn_mfma_f32_16x16x32_bf16(Bt[n][k], At[m][k], acc[ai][bj][m][n], 0, 0, 0); __builtin_amdgcn_s_setprio(0); } while (0)
; #define PG8_WAIT_V(n) asm volatile("s_waitcnt vmcnt(" #n ")" ::: "memory")
; #define PG8_WAIT_L(n) asm volatile("s_waitcnt lgkmcnt(" #n ")" ::: "memory")
; #define PG8_BAR __builtin_amdgcn_s_barrier()
; #define PG8_SCHED __builtin_amdgcn_sched_barrier(0)
; template <class Epi, class Sched, bool ALIGN_EPI = false, bool SP2 = false>
; __device__ __forceinline__ void gemm_phase(PG8_LAS unsigned char* lds, const Gemm g, const Sched& S, const Epi& E) {
;     ...
;             PG8_LDB(B0, 0, 0); PG8_LDB(B1, 0, 1); PG8_SCHED; PG8_LDA(At, 0, 0); PG8_STAGE(PG8_SA(1, 1), a1 + hstep, voffA);
;             PG8_WAIT_V(8); PG8_WAIT_L(0); PG8_BAR; PG8_MMA(0, 0, At, B0); PG8_MMA(0, 1, At, B1); PG8_BAR; PG8_SCHED;
;             PG8_LDA(At, 0, 1); PG8_STAGE(PG8_SB(0, 0), b2, voffB); PG8_STAGE(PG8_SB(0, 1), b2 + hstep, voffB); PG8_STAGE(PG8_SA(0, 0), a2, voffA);
;             PG8_WAIT_V(8); PG8_WAIT_L(0); PG8_BAR; PG8_MMA(1, 0, At, B0); PG8_MMA(1, 1, At, B1); PG8_BAR; PG8_SCHED;
.LBB0_507:
	s_add_u32 s28, s26, 0xfffc0080
	s_addc_u32 s29, s27, -1
	s_add_i32 s52, 0, 0x10000
	s_cmp_eq_u32 s68, 12
	s_cselect_b32 s31, s21, s29
	s_cselect_b32 s30, s86, s28
	s_cselect_b32 s29, s19, vcc_hi
	s_cselect_b32 s28, s87, vcc_lo
	s_add_i32 s69, 0, 0x14000
	v_add_u32_e32 v140, s52, v175
	v_add_u32_e32 v162, s69, v175
	ds_read_b128 v[128:131], v140
	ds_read_b128 v[132:135], v140 offset:1024
	ds_read_b128 v[136:139], v140 offset:2048
	ds_read_b128 v[140:143], v140 offset:3072
	ds_read_b128 v[144:147], v162
	ds_read_b128 v[148:151], v162 offset:1024
	ds_read_b128 v[178:181], v162 offset:2048
	ds_read_b128 v[182:185], v162 offset:3072
	s_add_i32 m0, s41, 0xc000
	ds_read_b128 v[186:189], v233
	ds_read_b128 v[190:193], v233 offset:1024
	ds_read_b128 v[194:197], v233 offset:2048
	ds_read_b128 v[198:201], v233 offset:3072
	ds_read_b128 v[202:205], v233 offset:4096
	ds_read_b128 v[206:209], v233 offset:5120
	ds_read_b128 v[210:213], v233 offset:6144
	ds_read_b128 v[214:217], v233 offset:7168
	global_load_lds_dwordx4 v158, s[26:27]
	s_add_i32 m0, s41, 0xe000
	s_nop 0
	global_load_lds_dwordx4 v176, s[26:27]
	s_waitcnt vmcnt(8)
	s_waitcnt lgkmcnt(0)
	s_barrier
	s_setprio 1
	s_waitcnt lgkmcnt(0)
	v_mfma_f32_16x16x32_bf16 v[124:127], v[128:131], v[186:189], v[124:127]
	v_mfma_f32_16x16x32_bf16 v[120:123], v[136:139], v[186:189], v[120:123]
	v_mfma_f32_16x16x32_bf16 v[108:111], v[128:131], v[194:197], v[108:111]
	v_mfma_f32_16x16x32_bf16 v[104:107], v[136:139], v[194:197], v[104:107]
	v_mfma_f32_16x16x32_bf16 v[92:95], v[128:131], v[202:205], v[92:95]
	v_mfma_f32_16x16x32_bf16 v[88:91], v[136:139], v[202:205], v[88:91]
	v_mfma_f32_16x16x32_bf16 v[76:79], v[128:131], v[210:213], v[76:79]
	v_mfma_f32_16x16x32_bf16 v[72:75], v[136:139], v[210:213], v[72:75]
	v_mfma_f32_16x16x32_bf16 v[124:127], v[132:135], v[190:193], v[124:127]
	v_mfma_f32_16x16x32_bf16 v[120:123], v[140:143], v[190:193], v[120:123]
	v_mfma_f32_16x16x32_bf16 v[108:111], v[132:135], v[198:201], v[108:111]
	v_mfma_f32_16x16x32_bf16 v[104:107], v[140:143], v[198:201], v[104:107]
	v_mfma_f32_16x16x32_bf16 v[92:95], v[132:135], v[206:209], v[92:95]
	v_mfma_f32_16x16x32_bf16 v[88:91], v[140:143], v[206:209], v[88:91]
	v_mfma_f32_16x16x32_bf16 v[76:79], v[132:135], v[214:217], v[76:79]
	v_mfma_f32_16x16x32_bf16 v[72:75], v[140:143], v[214:217], v[72:75]
	s_setprio 0
	s_setprio 1
	v_mfma_f32_16x16x32_bf16 v[116:119], v[144:147], v[186:189], v[116:119]
	v_mfma_f32_16x16x32_bf16 v[112:115], v[178:181], v[186:189], v[112:115]
	v_mfma_f32_16x16x32_bf16 v[100:103], v[144:147], v[194:197], v[100:103]
	v_mfma_f32_16x16x32_bf16 v[96:99], v[178:181], v[194:197], v[96:99]
	v_mfma_f32_16x16x32_bf16 v[84:87], v[144:147], v[202:205], v[84:87]
	v_mfma_f32_16x16x32_bf16 v[80:83], v[178:181], v[202:205], v[80:83]
	v_mfma_f32_16x16x32_bf16 v[68:71], v[144:147], v[210:213], v[68:71]
	v_mfma_f32_16x16x32_bf16 v[64:67], v[178:181], v[210:213], v[64:67]
	v_mfma_f32_16x16x32_bf16 v[116:119], v[148:151], v[190:193], v[116:119]
	v_mfma_f32_16x16x32_bf16 v[112:115], v[182:185], v[190:193], v[112:115]
	v_mfma_f32_16x16x32_bf16 v[100:103], v[148:151], v[198:201], v[100:103]
	v_mfma_f32_16x16x32_bf16 v[96:99], v[182:185], v[198:201], v[96:99]
	v_mfma_f32_16x16x32_bf16 v[84:87], v[148:151], v[206:209], v[84:87]
	v_mfma_f32_16x16x32_bf16 v[80:83], v[182:185], v[206:209], v[80:83]
	v_mfma_f32_16x16x32_bf16 v[68:71], v[148:151], v[214:217], v[68:71]
	v_mfma_f32_16x16x32_bf16 v[64:67], v[182:185], v[214:217], v[64:67]
	s_setprio 0
	s_barrier
	s_add_i32 s52, s52, s40
	v_lshl_add_u64 v[162:163], s[28:29], 0, v[160:161]
	s_mov_b32 m0, s52
	ds_read_b128 v[186:189], v233 offset:16384
	ds_read_b128 v[190:193], v233 offset:17408
	ds_read_b128 v[194:197], v233 offset:18432
	ds_read_b128 v[198:201], v233 offset:19456
	ds_read_b128 v[202:205], v233 offset:20480
	ds_read_b128 v[206:209], v233 offset:21504
	ds_read_b128 v[210:213], v233 offset:22528
	ds_read_b128 v[214:217], v233 offset:23552
	global_load_lds_dwordx4 v[162:163], off
	s_add_i32 m0, s52, 0x2000
	s_add_u32 s52, s28, 0x40000
	v_lshl_add_u64 v[164:165], s[28:29], 0, v[152:153]
	s_addc_u32 s53, s29, 0
	s_add_i32 s69, s69, s40
	global_load_lds_dwordx4 v[164:165], off
	s_mov_b32 m0, s69
	v_lshl_add_u64 v[220:221], s[30:31], 0, v[154:155]
	global_load_lds_dwordx4 v160, s[52:53]
	s_add_i32 m0, s69, 0x2000
	s_nop 0
	global_load_lds_dwordx4 v152, s[52:53]
	v_lshl_add_u64 v[218:219], s[30:31], 0, v[156:157]
	s_mov_b32 m0, s41
	s_nop 0
	global_load_lds_dwordx4 v[218:219], off
	s_mov_b32 m0, s42
	s_nop 0
	global_load_lds_dwordx4 v[220:221], off
	s_waitcnt vmcnt(8)
	s_waitcnt lgkmcnt(0)
	s_barrier
; #define PG8_STAGE(bufoff, gbase, voff) do { _Pragma("unroll") for (int _i = 0; _i < 2; ++_i) \
;         __builtin_amdgcn_global_load_lds((const unsigned*)((const char*)(gbase) + (voff)[_i]), (PG8_LAS unsigned*)(lds + (bufoff) + ldsw + _i * 8192), 16, 0, 0); } while (0)
; #define PG8_LDA(dst, b, h) do { _Pragma("unroll") for (int m = 0; m < 4; ++m) _Pragma("unroll") for (int k = 0; k < 2; ++k) dst[m][k] = *(const PG8_LAS bf16x8*)(lds + PG8_SA(b, h) + aoff + m * 2048 + k * 1024); } while (0)
; #define PG8_LDB(dst, b, h) do { _Pragma("unroll") for (int n = 0; n < 2; ++n) _Pragma("unroll") for (int k = 0; k < 2; ++k) dst[n][k] = *(const PG8_LAS bf16x8*)(lds + PG8_SB(b, h) + boff + n * 2048 + k * 1024); } while (0)
; #define PG8_MMA(ai, bj, At, Bt) do { __builtin_amdgcn_s_setprio(1); _Pragma("unroll") for (int m = 0; m < 4; ++m) _Pragma("unroll") for (int n = 0; n < 2; ++n) _Pragma("unroll") for (int k = 0; k < 2; ++k) \
;         acc[ai][bj][m][n] = __builtin_amdgcn_mfma_f32_16x16x32_bf16(Bt[n][k], At[m][k], acc[ai][bj][m][n], 0, 0, 0); __builtin_amdgcn_s_setprio(0); } while (0)
; #define PG8_WAIT_V(n) asm volatile("s_waitcnt vmcnt(" #n ")" ::: "memory")
; #define PG8_WAIT_L(n) asm volatile("s_waitcnt lgkmcnt(" #n ")" ::: "memory")
; #define PG8_BAR __builtin_amdgcn_s_barrier()
; #define PG8_SCHED __builtin_amdgcn_sched_barrier(0)
; template <class Epi, class Sched, bool ALIGN_EPI = false, bool SP2 = false>
; __device__ __forceinline__ void gemm_phase(PG8_LAS unsigned char* lds, const Gemm g, const Sched& S, const Epi& E) {
;     ...
;             PG8_WAIT_V(8); PG8_WAIT_L(0); PG8_BAR; PG8_MMA(1, 0, At, B0); PG8_MMA(1, 1, At, B1); PG8_BAR; PG8_SCHED;
;             PG8_LDB(B0, 1, 0); PG8_LDB(B1, 1, 1); PG8_SCHED; PG8_LDA(At, 1, 0); PG8_STAGE(PG8_SA(0, 1), a2 + hstep, voffA);
;             PG8_WAIT_V(8); PG8_WAIT_L(0); PG8_BAR; PG8_MMA(0, 0, At, B0); PG8_MMA(0, 1, At, B1); PG8_BAR; PG8_SCHED;
;             PG8_LDA(At, 1, 1); PG8_STAGE(PG8_SB(1, 0), b3, voffB); PG8_STAGE(PG8_SB(1, 1), b3 + hstep, voffB); PG8_STAGE(PG8_SA(1, 0), a3, voffA);
	s_setprio 1
	s_waitcnt lgkmcnt(0)
	v_mfma_f32_16x16x32_bf16 v[60:63], v[128:131], v[186:189], v[60:63]
	v_mfma_f32_16x16x32_bf16 v[56:59], v[136:139], v[186:189], v[56:59]
	v_mfma_f32_16x16x32_bf16 v[44:47], v[128:131], v[194:197], v[44:47]
	v_mfma_f32_16x16x32_bf16 v[40:43], v[136:139], v[194:197], v[40:43]
	v_mfma_f32_16x16x32_bf16 v[28:31], v[128:131], v[202:205], v[28:31]
	v_mfma_f32_16x16x32_bf16 v[24:27], v[136:139], v[202:205], v[24:27]
	v_mfma_f32_16x16x32_bf16 v[12:15], v[128:131], v[210:213], v[12:15]
	v_mfma_f32_16x16x32_bf16 v[8:11], v[136:139], v[210:213], v[8:11]
	v_mfma_f32_16x16x32_bf16 v[60:63], v[132:135], v[190:193], v[60:63]
	v_mfma_f32_16x16x32_bf16 v[56:59], v[140:143], v[190:193], v[56:59]
	v_mfma_f32_16x16x32_bf16 v[44:47], v[132:135], v[198:201], v[44:47]
	v_mfma_f32_16x16x32_bf16 v[40:43], v[140:143], v[198:201], v[40:43]
	v_mfma_f32_16x16x32_bf16 v[28:31], v[132:135], v[206:209], v[28:31]
	v_mfma_f32_16x16x32_bf16 v[24:27], v[140:143], v[206:209], v[24:27]
	v_mfma_f32_16x16x32_bf16 v[12:15], v[132:135], v[214:217], v[12:15]
	v_mfma_f32_16x16x32_bf16 v[8:11], v[140:143], v[214:217], v[8:11]
	s_setprio 0
	s_setprio 1
	v_mfma_f32_16x16x32_bf16 v[52:55], v[144:147], v[186:189], v[52:55]
	v_mfma_f32_16x16x32_bf16 v[48:51], v[178:181], v[186:189], v[48:51]
	v_mfma_f32_16x16x32_bf16 v[36:39], v[144:147], v[194:197], v[36:39]
	v_mfma_f32_16x16x32_bf16 v[32:35], v[178:181], v[194:197], v[32:35]
	v_mfma_f32_16x16x32_bf16 v[20:23], v[144:147], v[202:205], v[20:23]
	v_mfma_f32_16x16x32_bf16 v[16:19], v[178:181], v[202:205], v[16:19]
	v_mfma_f32_16x16x32_bf16 v[4:7], v[144:147], v[210:213], v[4:7]
	v_mfma_f32_16x16x32_bf16 v[0:3], v[178:181], v[210:213], v[0:3]
	v_mfma_f32_16x16x32_bf16 v[52:55], v[148:151], v[190:193], v[52:55]
	v_mfma_f32_16x16x32_bf16 v[48:51], v[182:185], v[190:193], v[48:51]
	v_mfma_f32_16x16x32_bf16 v[36:39], v[148:151], v[198:201], v[36:39]
	v_mfma_f32_16x16x32_bf16 v[32:35], v[182:185], v[198:201], v[32:35]
	v_mfma_f32_16x16x32_bf16 v[20:23], v[148:151], v[206:209], v[20:23]
	v_mfma_f32_16x16x32_bf16 v[16:19], v[182:185], v[206:209], v[16:19]
	v_mfma_f32_16x16x32_bf16 v[4:7], v[148:151], v[214:217], v[4:7]
	v_mfma_f32_16x16x32_bf16 v[0:3], v[182:185], v[214:217], v[0:3]
	s_setprio 0
	s_barrier
	s_add_i32 s52, 0, 0x18000
	s_add_i32 s53, 0, 0x1c000
	v_add_u32_e32 v140, s52, v175
	v_add_u32_e32 v182, s53, v175
	ds_read_b128 v[128:131], v140
	ds_read_b128 v[132:135], v140 offset:1024
	ds_read_b128 v[136:139], v140 offset:2048
	ds_read_b128 v[140:143], v140 offset:3072
	ds_read_b128 v[144:147], v182
	ds_read_b128 v[148:151], v182 offset:1024
	ds_read_b128 v[178:181], v182 offset:2048
	ds_read_b128 v[182:185], v182 offset:3072
	s_add_u32 s30, s30, 0x40000
	s_addc_u32 s31, s31, 0
	s_mov_b32 m0, s43
	ds_read_b128 v[186:189], v233 offset:32768
	ds_read_b128 v[190:193], v233 offset:33792
	ds_read_b128 v[194:197], v233 offset:34816
	ds_read_b128 v[198:201], v233 offset:35840
	ds_read_b128 v[202:205], v233 offset:36864
	ds_read_b128 v[206:209], v233 offset:37888
	ds_read_b128 v[210:213], v233 offset:38912
	ds_read_b128 v[214:217], v233 offset:39936
	global_load_lds_dwordx4 v156, s[30:31]
	s_mov_b32 m0, s44
	s_nop 0
	global_load_lds_dwordx4 v154, s[30:31]
	s_waitcnt vmcnt(8)
	s_waitcnt lgkmcnt(0)
	s_barrier
	s_setprio 1
	s_waitcnt lgkmcnt(0)
	v_mfma_f32_16x16x32_bf16 v[124:127], v[128:131], v[186:189], v[124:127]
	v_mfma_f32_16x16x32_bf16 v[120:123], v[136:139], v[186:189], v[120:123]
	v_mfma_f32_16x16x32_bf16 v[108:111], v[128:131], v[194:197], v[108:111]
	v_mfma_f32_16x16x32_bf16 v[104:107], v[136:139], v[194:197], v[104:107]
	v_mfma_f32_16x16x32_bf16 v[92:95], v[128:131], v[202:205], v[92:95]
	v_mfma_f32_16x16x32_bf16 v[88:91], v[136:139], v[202:205], v[88:91]
	v_mfma_f32_16x16x32_bf16 v[76:79], v[128:131], v[210:213], v[76:79]
	v_mfma_f32_16x16x32_bf16 v[72:75], v[136:139], v[210:213], v[72:75]
	v_mfma_f32_16x16x32_bf16 v[124:127], v[132:135], v[190:193], v[124:127]
	v_mfma_f32_16x16x32_bf16 v[120:123], v[140:143], v[190:193], v[120:123]
	v_mfma_f32_16x16x32_bf16 v[108:111], v[132:135], v[198:201], v[108:111]
	v_mfma_f32_16x16x32_bf16 v[104:107], v[140:143], v[198:201], v[104:107]
	v_mfma_f32_16x16x32_bf16 v[92:95], v[132:135], v[206:209], v[92:95]
	v_mfma_f32_16x16x32_bf16 v[88:91], v[140:143], v[206:209], v[88:91]
	v_mfma_f32_16x16x32_bf16 v[76:79], v[132:135], v[214:217], v[76:79]
	v_mfma_f32_16x16x32_bf16 v[72:75], v[140:143], v[214:217], v[72:75]
	s_setprio 0
	s_setprio 1
	v_mfma_f32_16x16x32_bf16 v[116:119], v[144:147], v[186:189], v[116:119]
	v_mfma_f32_16x16x32_bf16 v[112:115], v[178:181], v[186:189], v[112:115]
	v_mfma_f32_16x16x32_bf16 v[100:103], v[144:147], v[194:197], v[100:103]
	v_mfma_f32_16x16x32_bf16 v[96:99], v[178:181], v[194:197], v[96:99]
	v_mfma_f32_16x16x32_bf16 v[84:87], v[144:147], v[202:205], v[84:87]
	v_mfma_f32_16x16x32_bf16 v[80:83], v[178:181], v[202:205], v[80:83]
	v_mfma_f32_16x16x32_bf16 v[68:71], v[144:147], v[210:213], v[68:71]
	v_mfma_f32_16x16x32_bf16 v[64:67], v[178:181], v[210:213], v[64:67]
	v_mfma_f32_16x16x32_bf16 v[116:119], v[148:151], v[190:193], v[116:119]
	v_mfma_f32_16x16x32_bf16 v[112:115], v[182:185], v[190:193], v[112:115]
	v_mfma_f32_16x16x32_bf16 v[100:103], v[148:151], v[198:201], v[100:103]
	v_mfma_f32_16x16x32_bf16 v[96:99], v[182:185], v[198:201], v[96:99]
	v_mfma_f32_16x16x32_bf16 v[84:87], v[148:151], v[206:209], v[84:87]
	v_mfma_f32_16x16x32_bf16 v[80:83], v[182:185], v[206:209], v[80:83]
	v_mfma_f32_16x16x32_bf16 v[68:71], v[148:151], v[214:217], v[68:71]
	v_mfma_f32_16x16x32_bf16 v[64:67], v[182:185], v[214:217], v[64:67]
	s_setprio 0
	s_barrier
; #define PG8_STAGE(bufoff, gbase, voff) do { _Pragma("unroll") for (int _i = 0; _i < 2; ++_i) \
;         __builtin_amdgcn_global_load_lds((const unsigned*)((const char*)(gbase) + (voff)[_i]), (PG8_LAS unsigned*)(lds + (bufoff) + ldsw + _i * 8192), 16, 0, 0); } while (0)
; #define PG8_LDA(dst, b, h) do { _Pragma("unroll") for (int m = 0; m < 4; ++m) _Pragma("unroll") for (int k = 0; k < 2; ++k) dst[m][k] = *(const PG8_LAS bf16x8*)(lds + PG8_SA(b, h) + aoff + m * 2048 + k * 1024); } while (0)
; #define PG8_MMA(ai, bj, At, Bt) do { __builtin_amdgcn_s_setprio(1); _Pragma("unroll") for (int m = 0; m < 4; ++m) _Pragma("unroll") for (int n = 0; n < 2; ++n) _Pragma("unroll") for (int k = 0; k < 2; ++k) \
;         acc[ai][bj][m][n] = __builtin_amdgcn_mfma_f32_16x16x32_bf16(Bt[n][k], At[m][k], acc[ai][bj][m][n], 0, 0, 0); __builtin_amdgcn_s_setprio(0); } while (0)
; #define PG8_WAIT_V(n) asm volatile("s_waitcnt vmcnt(" #n ")" ::: "memory")
; #define PG8_WAIT_L(n) asm volatile("s_waitcnt lgkmcnt(" #n ")" ::: "memory")
; #define PG8_BAR __builtin_amdgcn_s_barrier()
; #define PG8_SCHED __builtin_amdgcn_sched_barrier(0)
; template <class Epi, class Sched, bool ALIGN_EPI = false, bool SP2 = false>
; __device__ __forceinline__ void gemm_phase(PG8_LAS unsigned char* lds, const Gemm g, const Sched& S, const Epi& E) {
;     ...
;             PG8_LDA(At, 1, 1); PG8_STAGE(PG8_SB(1, 0), b3, voffB); PG8_STAGE(PG8_SB(1, 1), b3 + hstep, voffB); PG8_STAGE(PG8_SA(1, 0), a3, voffA);
;             PG8_WAIT_V(8); PG8_WAIT_L(0); PG8_BAR; PG8_MMA(1, 0, At, B0); PG8_MMA(1, 1, At, B1); PG8_BAR; PG8_SCHED;
	s_add_i32 s30, s52, s40
	v_lshl_add_u64 v[162:163], v[162:163], 0, s[50:51]
	s_mov_b32 m0, s30
	ds_read_b128 v[186:189], v233 offset:49152
	ds_read_b128 v[190:193], v233 offset:50176
	ds_read_b128 v[194:197], v233 offset:51200
	ds_read_b128 v[198:201], v233 offset:52224
	ds_read_b128 v[202:205], v233 offset:53248
	ds_read_b128 v[206:209], v233 offset:54272
	ds_read_b128 v[210:213], v233 offset:55296
	ds_read_b128 v[214:217], v233 offset:56320
	global_load_lds_dwordx4 v[162:163], off
	s_add_i32 m0, s30, 0x2000
	s_add_u32 s28, s28, 0x40080
	v_lshl_add_u64 v[162:163], v[164:165], 0, s[50:51]
	s_addc_u32 s29, s29, 0
	s_add_i32 s30, s53, s40
	global_load_lds_dwordx4 v[162:163], off
	s_mov_b32 m0, s30
	s_nop 0
	global_load_lds_dwordx4 v160, s[28:29]
	s_add_i32 m0, s30, 0x2000
	s_nop 0
	global_load_lds_dwordx4 v152, s[28:29]
	v_lshl_add_u64 v[162:163], v[218:219], 0, s[50:51]
	s_mov_b32 m0, s46
	s_nop 0
	global_load_lds_dwordx4 v[162:163], off
	v_lshl_add_u64 v[162:163], v[220:221], 0, s[50:51]
	s_mov_b32 m0, s47
	s_nop 0
	global_load_lds_dwordx4 v[162:163], off
	s_waitcnt vmcnt(8)
	s_waitcnt lgkmcnt(0)
	s_barrier
	s_setprio 1
	s_waitcnt lgkmcnt(0)
	v_mfma_f32_16x16x32_bf16 v[60:63], v[128:131], v[186:189], v[60:63]
	v_mfma_f32_16x16x32_bf16 v[56:59], v[136:139], v[186:189], v[56:59]
	v_mfma_f32_16x16x32_bf16 v[44:47], v[128:131], v[194:197], v[44:47]
	v_mfma_f32_16x16x32_bf16 v[40:43], v[136:139], v[194:197], v[40:43]
	v_mfma_f32_16x16x32_bf16 v[28:31], v[128:131], v[202:205], v[28:31]
	v_mfma_f32_16x16x32_bf16 v[24:27], v[136:139], v[202:205], v[24:27]
	v_mfma_f32_16x16x32_bf16 v[12:15], v[128:131], v[210:213], v[12:15]
	v_mfma_f32_16x16x32_bf16 v[8:11], v[136:139], v[210:213], v[8:11]
	v_mfma_f32_16x16x32_bf16 v[60:63], v[132:135], v[190:193], v[60:63]
	v_mfma_f32_16x16x32_bf16 v[56:59], v[140:143], v[190:193], v[56:59]
	v_mfma_f32_16x16x32_bf16 v[44:47], v[132:135], v[198:201], v[44:47]
	v_mfma_f32_16x16x32_bf16 v[40:43], v[140:143], v[198:201], v[40:43]
	v_mfma_f32_16x16x32_bf16 v[28:31], v[132:135], v[206:209], v[28:31]
	v_mfma_f32_16x16x32_bf16 v[24:27], v[140:143], v[206:209], v[24:27]
	v_mfma_f32_16x16x32_bf16 v[12:15], v[132:135], v[214:217], v[12:15]
	v_mfma_f32_16x16x32_bf16 v[8:11], v[140:143], v[214:217], v[8:11]
	s_setprio 0
	s_setprio 1
	v_mfma_f32_16x16x32_bf16 v[52:55], v[144:147], v[186:189], v[52:55]
	v_mfma_f32_16x16x32_bf16 v[48:51], v[178:181], v[186:189], v[48:51]
	v_mfma_f32_16x16x32_bf16 v[36:39], v[144:147], v[194:197], v[36:39]
	v_mfma_f32_16x16x32_bf16 v[32:35], v[178:181], v[194:197], v[32:35]
	v_mfma_f32_16x16x32_bf16 v[20:23], v[144:147], v[202:205], v[20:23]
	v_mfma_f32_16x16x32_bf16 v[16:19], v[178:181], v[202:205], v[16:19]
	v_mfma_f32_16x16x32_bf16 v[4:7], v[144:147], v[210:213], v[4:7]
	v_mfma_f32_16x16x32_bf16 v[0:3], v[178:181], v[210:213], v[0:3]
	v_mfma_f32_16x16x32_bf16 v[52:55], v[148:151], v[190:193], v[52:55]
	v_mfma_f32_16x16x32_bf16 v[48:51], v[182:185], v[190:193], v[48:51]
	v_mfma_f32_16x16x32_bf16 v[36:39], v[148:151], v[198:201], v[36:39]
	v_mfma_f32_16x16x32_bf16 v[32:35], v[182:185], v[198:201], v[32:35]
	v_mfma_f32_16x16x32_bf16 v[20:23], v[148:151], v[206:209], v[20:23]
	v_mfma_f32_16x16x32_bf16 v[16:19], v[182:185], v[206:209], v[16:19]
	v_mfma_f32_16x16x32_bf16 v[4:7], v[148:151], v[214:217], v[4:7]
	v_mfma_f32_16x16x32_bf16 v[0:3], v[182:185], v[214:217], v[0:3]
	s_setprio 0
	s_barrier
	s_add_i32 s68, s68, 2
	s_add_u32 s26, s26, 0x100
	s_addc_u32 s27, s27, 0
	s_add_u32 vcc_lo, vcc_lo, 0x100
	s_addc_u32 vcc_hi, vcc_hi, 0
	s_cmp_gt_u32 s68, 13
	s_cbranch_scc0 .LBB0_507
	s_and_b64 vcc, exec, s[16:17]
	s_cbranch_vccz .LBB0_510
	s_barrier
